# RWKV chain: K=16 products use v_mfma_f32_16x16x16_f16 on the low operand pairs instead of zero-padding to K=32 (same f16 operands, f32 accumulate); 47 zero-padding v_mov per block become s_nop 0
# speedup vs baseline: 1.0471x; 1.0102x over previous
.LBB0_362:
	s_or_b64 exec, exec, s[28:29]
	s_waitcnt lgkmcnt(0)
	s_barrier
	ds_read_b128 v[40:43], v214 offset:9216
	ds_read_b128 v[48:51], v214 offset:18496
	ds_read_b128 v[56:59], v214 offset:9280
	ds_read_b128 v[60:63], v214 offset:23040
	ds_read_b128 v[36:39], v214 offset:18432
	s_nop 0
	s_nop 0
	s_nop 0
	ds_read_b128 v[64:67], v214 offset:13824
	s_waitcnt lgkmcnt(1)
	v_mfma_f32_16x16x32_f16 v[52:55], v[40:43], v[36:39], 0
	s_nop 0
	s_nop 0
	s_nop 0
	ds_read_b128 v[68:71], v214 offset:13888
	ds_read_b128 v[72:75], v214 offset:23104
	v_add_u32_e32 v80, 0x1000, v220
	s_nop 0
	v_mfma_f32_16x16x32_f16 v[52:55], v[56:59], v[48:51], v[52:55]
	s_nop 0
	s_nop 0
	s_nop 0
	v_mfma_f32_16x16x32_f16 v[44:47], v[36:39], v[40:43], 0
	s_nop 3
	v_cvt_f16_f32_e32 v0, v52
	v_cvt_f16_f32_e32 v1, v54
	v_cvt_f16_f32_e32 v2, v55
	v_mfma_f32_16x16x32_f16 v[44:47], v[48:51], v[56:59], v[44:47]
	v_cndmask_b32_e64 v79, 0, v0, s[12:13]
	v_cvt_f16_f32_e32 v0, v53
	v_cndmask_b32_e64 v54, 0, v1, s[18:19]
	s_nop 0
	v_mfma_f32_16x16x32_f16 v[40:43], v[60:63], v[40:43], 0
	v_cndmask_b32_e64 v55, 0, v2, s[22:23]
	s_nop 1
	v_cndmask_b32_e64 v76, 0, v44, s[10:11]
	v_cndmask_b32_e64 v77, 0, v45, s[14:15]
	s_nop 0
	s_waitcnt lgkmcnt(2)
	v_mfma_f32_16x16x32_f16 v[36:39], v[36:39], v[64:67], 0
	v_cndmask_b32_e64 v52, 0, v46, s[16:17]
	v_cndmask_b32_e64 v78, 0, v47, s[20:21]
	v_cndmask_b32_e64 v53, v0, 0, s[10:11]
	v_mfma_f32_16x16x32_f16 v[44:47], v[60:63], v[64:67], 0
	v_cvt_pk_f16_f32 v1, v52, v78
	v_cvt_pk_f16_f32 v0, v76, v77
	s_nop 0
	s_nop 0
	s_waitcnt lgkmcnt(0)
	v_mfma_f32_16x16x32_f16 v[60:63], v[72:75], v[56:59], v[40:43]
	v_add_f32_e32 v56, v215, v76
	v_add_f32_e32 v57, v217, v77
	v_add_f32_e32 v58, v218, v52
	v_mfma_f32_16x16x32_f16 v[40:43], v[48:51], v[68:71], v[36:39]
	v_add_f32_e32 v59, v219, v78
	v_cvt_pk_f16_f32 v67, v26, v27
	v_cvt_pk_f16_f32 v66, v24, v25
	v_pack_b32_f16 v37, v54, v55
	v_pack_b32_f16 v36, v79, v53
	s_nop 0
	s_nop 0
	v_mfma_f32_16x16x32_f16 v[52:55], v[72:75], v[68:71], v[44:47]
	ds_read2_b64 v[68:71], v220 offset0:8 offset1:12
	v_cvt_pk_f16_f32 v65, v30, v31
	v_cvt_pk_f16_f32 v64, v28, v29
	v_mfma_f32_16x16x16_f16 v[48:51], v[0:1], v[36:37], 0
	v_cvt_pk_f16_f32 v45, v58, v59
	v_cvt_pk_f16_f32 v44, v56, v57
	s_nop 0
	v_mfma_f32_16x16x16_f16 v[36:39], v[36:37], v[0:1], 0
	s_nop 0
	s_nop 2
	v_cvt_pk_f16_f32 v1, v50, v51
	v_cvt_pk_f16_f32 v0, v48, v49
	s_nop 0
	s_nop 0
	v_cvt_pk_f16_f32 v49, v38, v39
	v_cvt_pk_f16_f32 v48, v36, v37
	v_mfma_f32_16x16x16_f16 v[44:47], v[0:1], v[44:45], v[56:59]
	s_nop 0
	s_nop 0
	s_nop 0
	v_mfma_f32_16x16x16_f16 v[36:39], v[48:49], v[0:1], 0
	ds_read2_b64 v[128:131], v220 offset1:4
	v_cvt_pk_f16_f32 v59, v34, v35
	v_cvt_pk_f16_f32 v58, v32, v33
	v_cvt_pk_f16_f32 v57, v22, v23
	v_mfma_f32_16x16x16_f16 v[48:51], v[0:1], v[48:49], 0
	v_cvt_pk_f16_f32 v56, v20, v21
	s_nop 2
	v_cvt_pk_f16_f32 v1, v38, v39
	v_cvt_pk_f16_f32 v0, v36, v37
	v_cvt_pk_f16_f32 v37, v46, v47
	v_cvt_pk_f16_f32 v36, v44, v45
	s_nop 0
	s_nop 0
	v_cvt_f16_f32_e32 v52, v52
	s_add_i32 s27, s26, 1
	v_mfma_f32_16x16x16_f16 v[44:47], v[0:1], v[36:37], v[44:47]
	v_cvt_pk_f16_f32 v37, v50, v51
	v_cvt_pk_f16_f32 v36, v48, v49
	s_nop 0
	s_nop 0
	v_mfma_f32_16x16x16_f16 v[36:39], v[36:37], v[0:1], 0
	s_nop 2
	v_cvt_pk_f16_f32 v1, v46, v47
	v_cvt_pk_f16_f32 v0, v44, v45
	s_nop 2
	v_cvt_pk_f16_f32 v49, v38, v39
	v_cvt_pk_f16_f32 v48, v36, v37
	s_nop 0
	s_nop 0
	s_waitcnt lgkmcnt(0)
	v_mfma_f32_16x16x32_f16 v[36:39], v[128:131], v[56:59], 0
	v_mfma_f32_16x16x16_f16 v[44:47], v[48:49], v[0:1], v[44:47]
	v_cvt_f16_f32_e32 v0, v60
	v_cvt_f16_f32_e32 v1, v61
	v_cvt_f16_f32_e32 v2, v62
	v_cvt_f16_f32_e32 v48, v63
	v_mfma_f32_16x16x32_f16 v[76:79], v[68:71], v[64:67], v[36:39]
	ds_read2_b64 v[72:75], v80 offset0:64 offset1:68
	ds_read2st64_b64 v[132:135], v221 offset0:20 offset1:25
	ds_read2_b64 v[68:71], v80 offset0:72 offset1:76
	s_nop 0
	s_nop 0
	v_cndmask_b32_e64 v0, 0, v0, s[10:11]
	v_cndmask_b32_e64 v49, 0, v1, s[14:15]
	v_cndmask_b32_e64 v1, 0, v2, s[16:17]
	v_cndmask_b32_e64 v2, 0, v48, s[20:21]
	v_pack_b32_f16 v1, v1, v2
	v_pack_b32_f16 v0, v0, v49
	s_nop 0
	s_nop 0
	s_waitcnt lgkmcnt(1)
	v_mov_b32_e32 v60, v132
	v_mov_b32_e32 v61, v133
	ds_read2_b64 v[128:131], v236 offset1:80
	s_nop 0
	s_nop 0
	v_cvt_f16_f32_e32 v36, v40
	ds_read_b128 v[136:139], v180
	v_cvt_f16_f32_e32 v40, v42
	v_mfma_f32_16x16x16_f16 v[48:51], v[0:1], v[60:61], v[76:79]
	v_cvt_pk_f16_f32 v1, v46, v47
	v_cvt_pk_f16_f32 v0, v44, v45
	v_cvt_f16_f32_e32 v37, v41
	s_nop 0
	s_nop 0
	s_nop 2
	v_cvt_pk_f16_f32 v77, v50, v51
	v_cvt_pk_f16_f32 v76, v48, v49
	v_cndmask_b32_e64 v88, v40, 0, s[18:19]
	v_mfma_f32_16x16x32_f16 v[56:59], v[72:75], v[56:59], 0
	v_cndmask_b32_e64 v36, v36, 0, s[12:13]
	v_cndmask_b32_e64 v37, 0, v37, s[10:11]
	s_nop 0
	v_mfma_f32_16x16x16_f16 v[44:47], v[0:1], v[76:77], 0
	ds_read_b64 v[76:77], v222 offset:5120
	ds_read_b128 v[140:143], v180 offset:64
	s_nop 0
	s_waitcnt lgkmcnt(4)
	v_mfma_f32_16x16x32_f16 v[56:59], v[68:71], v[64:67], v[56:59]
	s_nop 5
	v_cvt_pk_f16_f32 v1, v46, v47
	v_cvt_pk_f16_f32 v0, v44, v45
	s_nop 0
	s_nop 0
	s_nop 0
	s_nop 0
	s_waitcnt lgkmcnt(3)
	v_mov_b32_e32 v80, v128
	v_mov_b32_e32 v81, v129
	ds_read_b64 v[44:45], v223 offset:5120
	ds_read2_b64 v[144:147], v236 offset0:160 offset1:240
	s_nop 0
	s_waitcnt lgkmcnt(4)
	v_pk_mul_f32 v[50:51], v[22:23], v[138:139]
	v_pk_mul_f32 v[48:49], v[20:21], v[136:137]
	ds_read_b128 v[136:139], v180 offset:128
	s_nop 1
	v_mfma_f32_16x16x16_f16 v[48:51], v[80:81], v[0:1], v[48:51]
	v_cvt_f16_f32_e32 v80, v43
	v_cndmask_b32_e64 v89, v80, 0, s[22:23]
	s_nop 0
	s_waitcnt lgkmcnt(4)
	v_mfma_f32_16x16x16_f16 v[40:43], v[76:77], v[60:61], v[48:51]
	s_nop 3
	s_nop 0
	s_nop 0
	ds_read_b64 v[80:81], v224 offset:5120
	v_mov_b32_e32 v76, v130
	v_mov_b32_e32 v77, v131
	s_nop 0
	s_nop 0
	s_waitcnt lgkmcnt(4)
	v_pk_mul_f32 v[50:51], v[34:35], v[142:143]
	v_pk_mul_f32 v[48:49], v[32:33], v[140:141]
	s_nop 0
	ds_read_b128 v[128:131], v180 offset:192
	s_nop 0
	v_mfma_f32_16x16x16_f16 v[48:51], v[76:77], v[0:1], v[48:51]
	s_nop 0
	s_nop 0
	s_waitcnt lgkmcnt(3)
	v_mov_b32_e32 v84, v144
	v_mfma_f32_16x16x16_f16 v[48:51], v[44:45], v[60:61], v[48:51]
	s_nop 0
	s_nop 0
	v_mov_b32_e32 v85, v145
	v_pack_b32_f16 v77, v88, v89
	v_mov_b32_e32 v88, v146
	s_nop 0
	s_waitcnt lgkmcnt(2)
	v_pk_mul_f32 v[46:47], v[30:31], v[138:139]
	v_pk_mul_f32 v[44:45], v[28:29], v[136:137]
	v_mov_b32_e32 v89, v147
	v_pack_b32_f16 v76, v36, v37
	v_mfma_f32_16x16x16_f16 v[44:47], v[84:85], v[0:1], v[44:47]
	ds_read_b64 v[84:85], v225 offset:5120
	v_cndmask_b32_e64 v36, v52, 0, s[12:13]
	v_cvt_f16_f32_e32 v37, v53
	v_cndmask_b32_e64 v37, 0, v37, s[10:11]
	s_nop 0
	s_waitcnt lgkmcnt(2)
	v_mfma_f32_16x16x16_f16 v[44:47], v[80:81], v[60:61], v[44:47]
	s_nop 0
	s_nop 0
	v_pack_b32_f16 v72, v36, v37
	ds_read_b128 v[68:71], v226 offset:9216
	ds_read_b128 v[94:97], v226 offset:9280
	s_nop 0
	s_waitcnt lgkmcnt(3)
	v_pk_mul_f32 v[82:83], v[26:27], v[130:131]
	ds_read_b128 v[64:67], v226 offset:18432
	v_pk_mul_f32 v[80:81], v[24:25], v[128:129]
	s_nop 0
	ds_read_b128 v[98:101], v226 offset:23104
	v_mfma_f32_16x16x16_f16 v[78:81], v[88:89], v[0:1], v[80:83]
	ds_read_b128 v[90:93], v226 offset:18496
	s_nop 1
	v_cvt_f16_f32_e32 v82, v54
	v_cvt_f16_f32_e32 v83, v55
	s_nop 0
	s_waitcnt lgkmcnt(5)
	v_mfma_f32_16x16x16_f16 v[52:55], v[84:85], v[60:61], v[78:81]
	ds_read_b128 v[86:89], v226 offset:13824
	s_nop 1
	v_cndmask_b32_e64 v78, v82, 0, s[18:19]
	v_cndmask_b32_e64 v79, v83, 0, s[22:23]
	v_pack_b32_f16 v73, v78, v79
	s_nop 0
	s_nop 0
	v_add_u32_e32 v80, s77, v122
	v_add_u32_e32 v81, s76, v235
	v_mfma_f32_16x16x16_f16 v[56:59], v[76:77], v[0:1], v[56:59]
	ds_read_b128 v[76:79], v226 offset:23040
	v_subrev_u32_e32 v102, 64, v80
	v_add_u32_e32 v0, 0xff, v81
	v_mfma_f32_16x16x16_f16 v[58:61], v[72:73], v[60:61], v[56:59]
	v_cndmask_b32_e64 v0, v0, v102, s[2:3]
	v_add_u32_e32 v0, v0, v173
	v_mad_i64_i32 v[0:1], s[28:29], v0, s91, v[126:127]
	s_nop 0
	s_waitcnt lgkmcnt(4)
	v_mfma_f32_16x16x32_f16 v[82:85], v[68:71], v[64:67], 0
	s_nop 2
	v_cvt_f16_f32_e32 v2, v58
	v_cvt_f16_f32_e32 v60, v60
	ds_read_b128 v[128:131], v226 offset:13888
	global_store_short v[0:1], v2, off
	v_subrev_u32_e32 v0, 63, v80
	v_xad_u32 v1, v102, -2, v166
	v_cvt_f16_f32_e32 v2, v59
	s_nop 0
	v_mfma_f32_16x16x32_f16 v[72:75], v[64:67], v[68:71], 0
	v_cndmask_b32_e64 v0, v1, v0, s[2:3]
	v_add_u32_e32 v0, v0, v173
	v_mad_i64_i32 v[0:1], s[28:29], v0, s91, v[126:127]
	s_nop 0
	s_waitcnt lgkmcnt(2)
	v_mfma_f32_16x16x32_f16 v[62:65], v[64:67], v[86:89], 0
	global_store_short v[0:1], v2, off
	v_subrev_u32_e32 v0, 62, v80
	v_xad_u32 v1, v102, -3, v166
	v_mfma_f32_16x16x32_f16 v[82:85], v[94:97], v[90:93], v[82:85]
	v_cndmask_b32_e64 v36, v1, v0, s[2:3]
	v_add_u32_e32 v36, v36, v173
	s_nop 0
	s_waitcnt lgkmcnt(1)
	v_mfma_f32_16x16x32_f16 v[68:71], v[76:79], v[68:71], 0
	v_mfma_f32_16x16x32_f16 v[86:89], v[76:79], v[86:89], 0
	s_nop 2
	v_cvt_f16_f32_e32 v1, v82
	v_cvt_f16_f32_e32 v2, v83
	v_cvt_f16_f32_e32 v66, v85
	v_mfma_f32_16x16x32_f16 v[72:75], v[90:93], v[94:97], v[72:75]
	s_nop 0
	v_cndmask_b32_e64 v66, 0, v66, s[22:23]
	s_nop 0
	s_waitcnt lgkmcnt(0)
	v_mfma_f32_16x16x32_f16 v[76:79], v[90:93], v[128:131], v[62:65]
	s_nop 0
	s_nop 2
	v_cndmask_b32_e64 v0, 0, v72, s[10:11]
	v_cndmask_b32_e64 v37, 0, v73, s[14:15]
	v_cvt_f16_f32_e32 v63, v84
	v_mfma_f32_16x16x32_f16 v[94:97], v[98:101], v[94:97], v[68:71]
	v_cndmask_b32_e64 v64, 0, v74, s[16:17]
	v_cndmask_b32_e64 v65, 0, v75, s[20:21]
	v_cndmask_b32_e64 v63, 0, v63, s[18:19]
	v_cndmask_b32_e64 v68, 0, v1, s[12:13]
	v_cndmask_b32_e64 v69, v2, 0, s[10:11]
	v_add_f32_e32 v62, v215, v0
	v_cvt_pk_f16_f32 v1, v64, v65
	v_cvt_pk_f16_f32 v0, v0, v37
	s_nop 0
	v_pack_b32_f16 v67, v63, v66
	v_pack_b32_f16 v66, v68, v69
	s_nop 0
	s_nop 0
	v_add_f32_e32 v63, v217, v37
	v_add_f32_e32 v64, v218, v64
	v_mfma_f32_16x16x16_f16 v[70:73], v[0:1], v[66:67], 0
	v_add_f32_e32 v65, v219, v65
	v_cvt_pk_f16_f32 v83, v64, v65
	v_cvt_pk_f16_f32 v82, v62, v63
	v_mfma_f32_16x16x16_f16 v[66:69], v[66:67], v[0:1], 0
	s_nop 0
	s_nop 2
	v_cvt_pk_f16_f32 v0, v70, v71
	s_nop 0
	s_nop 0
	v_cvt_pk_f16_f32 v1, v72, v73
	v_cvt_pk_f16_f32 v69, v68, v69
	v_cvt_pk_f16_f32 v68, v66, v67
	v_mfma_f32_16x16x16_f16 v[62:65], v[0:1], v[82:83], v[62:65]
	v_mad_i64_i32 v[36:37], s[28:29], v36, s91, v[126:127]
	global_store_short v[36:37], v60, off
	v_mfma_f32_16x16x16_f16 v[72:75], v[68:69], v[0:1], 0
	v_cvt_f16_f32_e32 v82, v61
	v_subrev_u32_e32 v36, 61, v80
	v_xad_u32 v37, v102, -4, v166
	v_mfma_f32_16x16x16_f16 v[66:69], v[0:1], v[68:69], 0
	s_nop 0
	v_cvt_pk_f16_f32 v71, v64, v65
	s_nop 1
	v_cvt_pk_f16_f32 v1, v74, v75
	v_cvt_pk_f16_f32 v0, v72, v73
	ds_read2_b64 v[136:139], v227 offset1:4
	v_mfma_f32_16x16x32_f16 v[56:59], v[98:101], v[128:131], v[86:89]
	v_cvt_pk_f16_f32 v70, v62, v63
	s_nop 0
	s_nop 0
	v_cvt_pk_f16_f32 v85, v68, v69
	ds_read2_b64 v[128:131], v227 offset0:8 offset1:12
	v_cvt_pk_f16_f32 v84, v66, v67
	s_nop 0
	s_nop 0
	v_mfma_f32_16x16x16_f16 v[88:91], v[0:1], v[70:71], v[62:65]
	s_nop 0
	s_nop 0
	v_cndmask_b32_e64 v36, v37, v36, s[2:3]
	v_mfma_f32_16x16x16_f16 v[60:63], v[84:85], v[0:1], 0
	v_add_u32_e32 v83, v36, v173
	s_nop 2
	v_cvt_pk_f16_f32 v1, v90, v91
	v_cvt_pk_f16_f32 v0, v88, v89
	v_cvt_pk_f16_f32 v67, v54, v55
	v_cvt_pk_f16_f32 v66, v52, v53
	v_cvt_pk_f16_f32 v85, v62, v63
	v_cvt_pk_f16_f32 v84, v60, v61
	v_cvt_pk_f16_f32 v63, v50, v51
	v_cvt_pk_f16_f32 v62, v48, v49
	v_cvt_pk_f16_f32 v61, v42, v43
	v_cvt_pk_f16_f32 v60, v40, v41
	v_cvt_pk_f16_f32 v65, v46, v47
	v_cvt_pk_f16_f32 v64, v44, v45
	s_nop 0
	s_waitcnt lgkmcnt(1)
	v_mfma_f32_16x16x32_f16 v[68:71], v[136:139], v[60:63], 0
	v_add_u32_e32 v36, 0x1000, v227
	s_nop 0
	v_cvt_f16_f32_e32 v76, v76
	s_nop 0
	s_waitcnt lgkmcnt(0)
	v_mfma_f32_16x16x32_f16 v[98:101], v[128:131], v[64:67], v[68:71]
	ds_read2_b64 v[72:75], v36 offset0:64 offset1:68
	s_nop 1
	ds_read2_b64 v[68:71], v36 offset0:72 offset1:76
	v_cvt_f16_f32_e32 v36, v97
	v_cvt_f16_f32_e32 v97, v77
	v_mfma_f32_16x16x16_f16 v[84:87], v[84:85], v[0:1], v[88:91]
	v_cvt_f16_f32_e32 v0, v94
	v_cvt_f16_f32_e32 v1, v95
	v_cvt_f16_f32_e32 v2, v96
	v_cndmask_b32_e64 v96, v76, 0, s[12:13]
	v_cndmask_b32_e64 v0, 0, v0, s[10:11]
	v_cndmask_b32_e64 v37, 0, v1, s[14:15]
	v_cndmask_b32_e64 v1, 0, v2, s[16:17]
	v_cndmask_b32_e64 v2, 0, v36, s[20:21]
	v_pack_b32_f16 v1, v1, v2
	v_pack_b32_f16 v0, v0, v37
	s_nop 0
	v_mov_b32_e32 v36, v134
	v_mov_b32_e32 v37, v135
	s_nop 0
	s_nop 0
	v_mov_b32_e32 v94, v3
	v_mov_b32_e32 v95, v3
	v_mfma_f32_16x16x16_f16 v[88:91], v[0:1], v[36:37], v[98:101]
	v_cvt_pk_f16_f32 v1, v86, v87
	v_cvt_pk_f16_f32 v0, v84, v85
	v_cvt_f16_f32_e32 v56, v56
	v_cvt_f16_f32_e32 v98, v78
	v_cvt_f16_f32_e32 v99, v79
	s_nop 2
	v_cvt_pk_f16_f32 v91, v90, v91
	v_cvt_pk_f16_f32 v90, v88, v89
	v_cndmask_b32_e64 v97, 0, v97, s[10:11]
	v_cndmask_b32_e64 v98, v98, 0, s[18:19]
	v_mfma_f32_16x16x16_f16 v[84:87], v[0:1], v[90:91], 0
	v_add_u32_e32 v2, 0x800, v236
	ds_read2_b64 v[128:131], v2 offset0:64 offset1:144
	ds_read_b128 v[76:79], v180 offset:256
	v_mov_b32_e32 v90, v3
	v_mov_b32_e32 v91, v3
	v_cndmask_b32_e64 v99, v99, 0, s[22:23]
	ds_read_b64 v[88:89], v228 offset:5120
	ds_read_b128 v[132:135], v180 offset:320
	s_nop 3
	v_cvt_pk_f16_f32 v1, v86, v87
	v_cvt_pk_f16_f32 v0, v84, v85
	s_nop 0
	s_nop 0
	s_nop 0
	s_nop 0
	s_nop 0
	s_waitcnt lgkmcnt(3)
	v_mov_b32_e32 v92, v128
	v_mov_b32_e32 v93, v129
	ds_read_b64 v[84:85], v229 offset:5120
	s_nop 0
	s_waitcnt lgkmcnt(3)
	v_pk_mul_f32 v[42:43], v[42:43], v[78:79]
	v_pk_mul_f32 v[40:41], v[40:41], v[76:77]
	s_nop 0
	s_nop 0
	v_mfma_f32_16x16x16_f16 v[40:43], v[92:93], v[0:1], v[40:43]
	s_nop 0
	s_waitcnt lgkmcnt(1)
	v_pk_mul_f32 v[48:49], v[48:49], v[132:133]
	v_add_u32_e32 v76, 0xc00, v236
	ds_read2_b64 v[136:139], v76 offset0:96 offset1:176
	ds_read_b128 v[140:143], v180 offset:384
	v_mfma_f32_16x16x16_f16 v[40:43], v[88:89], v[36:37], v[40:43]
	v_mov_b32_e32 v88, v130
	v_mov_b32_e32 v89, v131
	v_pk_mul_f32 v[50:51], v[50:51], v[134:135]
	s_nop 0
	s_nop 0
	s_nop 0
	v_mfma_f32_16x16x16_f16 v[48:51], v[88:89], v[0:1], v[48:51]
	ds_read_b64 v[88:89], v230 offset:5120
	s_nop 0
	s_waitcnt lgkmcnt(2)
	v_mov_b32_e32 v92, v136
	v_mfma_f32_16x16x16_f16 v[48:51], v[84:85], v[36:37], v[48:51]
	s_nop 0
	s_nop 0
	v_mov_b32_e32 v93, v137
	v_pack_b32_f16 v76, v96, v97
	v_cndmask_b32_e64 v96, v56, 0, s[12:13]
	s_nop 0
	s_waitcnt lgkmcnt(1)
	v_pk_mul_f32 v[46:47], v[46:47], v[142:143]
	v_pk_mul_f32 v[44:45], v[44:45], v[140:141]
	ds_read_b128 v[84:87], v180 offset:448
	v_cvt_f16_f32_e32 v56, v57
	v_cvt_f16_f32_e32 v57, v58
	v_mfma_f32_16x16x16_f16 v[44:47], v[92:93], v[0:1], v[44:47]
	v_cvt_f16_f32_e32 v58, v59
	v_mov_b32_e32 v92, v138
	v_mov_b32_e32 v93, v139
	s_nop 0
	s_waitcnt lgkmcnt(1)
	v_mfma_f32_16x16x16_f16 v[44:47], v[88:89], v[36:37], v[44:47]
	ds_read_b64 v[88:89], v231 offset:5120
	s_nop 0
	s_nop 0
	v_cndmask_b32_e64 v78, v57, 0, s[18:19]
	v_cndmask_b32_e64 v79, v58, 0, s[22:23]
	v_pack_b32_f16 v77, v98, v99
	s_nop 0
	s_waitcnt lgkmcnt(1)
	v_pk_mul_f32 v[52:53], v[52:53], v[84:85]
	v_cndmask_b32_e64 v84, 0, v56, s[10:11]
	v_mfma_f32_16x16x32_f16 v[56:59], v[72:75], v[60:63], 0
	v_pack_b32_f16 v61, v78, v79
	v_mov_b32_e32 v78, v3
	v_mov_b32_e32 v79, v3
	v_mfma_f32_16x16x32_f16 v[56:59], v[68:71], v[64:67], v[56:59]
	v_mul_f32_e64 v54, v54, v86
	v_mul_f32_e64 v55, v55, v87
	v_pack_b32_f16 v60, v96, v84
	v_mov_b32_e32 v62, v3
	v_mov_b32_e32 v63, v3
	v_mfma_f32_16x16x16_f16 v[52:55], v[92:93], v[0:1], v[52:55]
	v_mfma_f32_16x16x16_f16 v[56:59], v[76:77], v[0:1], v[56:59]
	v_mad_i64_i32 v[0:1], s[28:29], v83, s91, v[126:127]
	global_store_short v[0:1], v82, off
	s_nop 0
	s_waitcnt lgkmcnt(0)
	v_mfma_f32_16x16x16_f16 v[52:55], v[88:89], v[36:37], v[52:55]
	v_subrev_u32_e32 v0, 48, v80
	v_add_u32_e32 v1, 0xef, v81
	v_cndmask_b32_e64 v0, v1, v0, s[2:3]
	v_mfma_f32_16x16x16_f16 v[36:39], v[60:61], v[36:37], v[56:59]
	v_add_u32_e32 v0, v0, v173
	v_mad_i64_i32 v[0:1], s[28:29], v0, s91, v[126:127]
	s_nop 5
	v_cvt_f16_f32_e32 v2, v36
	global_store_short v[0:1], v2, off
	v_subrev_u32_e32 v0, 47, v80
	v_add_u32_e32 v1, 0xee, v81
	v_cvt_f16_f32_e32 v2, v37
	v_cndmask_b32_e64 v0, v1, v0, s[2:3]
	v_add_u32_e32 v0, v0, v173
	v_mad_i64_i32 v[0:1], s[28:29], v0, s91, v[126:127]
	global_store_short v[0:1], v2, off
	v_subrev_u32_e32 v0, 46, v80
	v_add_u32_e32 v1, 0xed, v81
	v_cvt_f16_f32_e32 v2, v38
	v_cndmask_b32_e64 v0, v1, v0, s[2:3]
	v_add_u32_e32 v0, v0, v173
	v_mad_i64_i32 v[0:1], s[28:29], v0, s91, v[126:127]
	global_store_short v[0:1], v2, off
	v_subrev_u32_e32 v0, 45, v80
	v_add_u32_e32 v1, 0xec, v81
	v_cndmask_b32_e64 v0, v1, v0, s[2:3]
	v_cvt_f16_f32_e32 v2, v39
	v_add_u32_e32 v0, v0, v173
	v_mad_i64_i32 v[0:1], s[28:29], v0, s91, v[126:127]
	s_mov_b64 s[28:29], 0
	global_store_short v[0:1], v2, off

.LBB0_462:
	s_or_b64 exec, exec, s[26:27]
	s_waitcnt lgkmcnt(0)
	s_barrier
	ds_read_b128 v[40:43], v210 offset:9216
	ds_read_b128 v[48:51], v210 offset:18496
	ds_read_b128 v[56:59], v210 offset:9280
	ds_read_b128 v[60:63], v210 offset:23040
	ds_read_b128 v[36:39], v210 offset:18432
	s_nop 0
	s_nop 0
	s_nop 0
	ds_read_b128 v[64:67], v210 offset:13824
	s_waitcnt lgkmcnt(1)
	v_mfma_f32_16x16x32_f16 v[52:55], v[40:43], v[36:39], 0
	s_nop 0
	s_nop 0
	s_nop 0
	ds_read_b128 v[68:71], v210 offset:13888
	ds_read_b128 v[72:75], v210 offset:23104
	v_add_u32_e32 v80, 0x1000, v215
	s_nop 0
	v_mfma_f32_16x16x32_f16 v[52:55], v[56:59], v[48:51], v[52:55]
	s_nop 0
	s_nop 0
	s_nop 0
	v_mfma_f32_16x16x32_f16 v[44:47], v[36:39], v[40:43], 0
	s_nop 3
	v_cvt_f16_f32_e32 v0, v52
	v_cvt_f16_f32_e32 v1, v54
	v_cvt_f16_f32_e32 v2, v55
	v_mfma_f32_16x16x32_f16 v[44:47], v[48:51], v[56:59], v[44:47]
	v_cndmask_b32_e64 v79, 0, v0, s[12:13]
	v_cvt_f16_f32_e32 v0, v53
	v_cndmask_b32_e64 v54, 0, v1, s[18:19]
	s_nop 0
	v_mfma_f32_16x16x32_f16 v[40:43], v[60:63], v[40:43], 0
	v_cndmask_b32_e64 v55, 0, v2, s[22:23]
	s_nop 1
	v_cndmask_b32_e64 v76, 0, v44, s[10:11]
	v_cndmask_b32_e64 v77, 0, v45, s[14:15]
	s_nop 0
	s_waitcnt lgkmcnt(2)
	v_mfma_f32_16x16x32_f16 v[36:39], v[36:39], v[64:67], 0
	v_cndmask_b32_e64 v52, 0, v46, s[16:17]
	v_cndmask_b32_e64 v78, 0, v47, s[20:21]
	v_cndmask_b32_e64 v53, v0, 0, s[10:11]
	v_mfma_f32_16x16x32_f16 v[44:47], v[60:63], v[64:67], 0
	v_cvt_pk_f16_f32 v1, v52, v78
	v_cvt_pk_f16_f32 v0, v76, v77
	s_nop 0
	s_nop 0
	s_waitcnt lgkmcnt(0)
	v_mfma_f32_16x16x32_f16 v[60:63], v[72:75], v[56:59], v[40:43]
	v_add_f32_e32 v56, v211, v76
	v_add_f32_e32 v57, v212, v77
	v_add_f32_e32 v58, v213, v52
	v_mfma_f32_16x16x32_f16 v[40:43], v[48:51], v[68:71], v[36:39]
	v_add_f32_e32 v59, v214, v78
	v_cvt_pk_f16_f32 v67, v18, v19
	v_cvt_pk_f16_f32 v66, v16, v17
	v_pack_b32_f16 v37, v54, v55
	v_pack_b32_f16 v36, v79, v53
	s_nop 0
	s_nop 0
	v_mfma_f32_16x16x32_f16 v[52:55], v[72:75], v[68:71], v[44:47]
	ds_read2_b64 v[68:71], v215 offset0:8 offset1:12
	v_cvt_pk_f16_f32 v65, v14, v15
	v_cvt_pk_f16_f32 v64, v12, v13
	v_mfma_f32_16x16x16_f16 v[48:51], v[0:1], v[36:37], 0
	v_cvt_pk_f16_f32 v45, v58, v59
	v_cvt_pk_f16_f32 v44, v56, v57
	s_nop 0
	v_mfma_f32_16x16x16_f16 v[36:39], v[36:37], v[0:1], 0
	s_nop 0
	s_nop 2
	v_cvt_pk_f16_f32 v1, v50, v51
	v_cvt_pk_f16_f32 v0, v48, v49
	s_nop 0
	s_nop 0
	v_cvt_pk_f16_f32 v49, v38, v39
	v_cvt_pk_f16_f32 v48, v36, v37
	v_mfma_f32_16x16x16_f16 v[44:47], v[0:1], v[44:45], v[56:59]
	s_nop 0
	s_nop 0
	s_nop 0
	v_mfma_f32_16x16x16_f16 v[36:39], v[48:49], v[0:1], 0
	ds_read2_b64 v[126:129], v215 offset1:4
	v_cvt_pk_f16_f32 v59, v10, v11
	v_cvt_pk_f16_f32 v58, v8, v9
	v_cvt_pk_f16_f32 v57, v6, v7
	v_mfma_f32_16x16x16_f16 v[48:51], v[0:1], v[48:49], 0
	v_cvt_pk_f16_f32 v56, v4, v5
	s_nop 2
	v_cvt_pk_f16_f32 v1, v38, v39
	v_cvt_pk_f16_f32 v0, v36, v37
	v_cvt_pk_f16_f32 v37, v46, v47
	v_cvt_pk_f16_f32 v36, v44, v45
	s_nop 0
	s_nop 0
	v_cvt_f16_f32_e32 v52, v52
	s_add_i32 s28, s76, 1
	v_mfma_f32_16x16x16_f16 v[44:47], v[0:1], v[36:37], v[44:47]
	v_cvt_pk_f16_f32 v37, v50, v51
	v_cvt_pk_f16_f32 v36, v48, v49
	s_nop 0
	s_nop 0
	v_mfma_f32_16x16x16_f16 v[36:39], v[36:37], v[0:1], 0
	s_nop 2
	v_cvt_pk_f16_f32 v1, v46, v47
	v_cvt_pk_f16_f32 v0, v44, v45
	s_nop 2
	v_cvt_pk_f16_f32 v49, v38, v39
	v_cvt_pk_f16_f32 v48, v36, v37
	s_nop 0
	s_nop 0
	s_waitcnt lgkmcnt(0)
	v_mfma_f32_16x16x32_f16 v[36:39], v[126:129], v[56:59], 0
	v_mfma_f32_16x16x16_f16 v[44:47], v[48:49], v[0:1], v[44:47]
	v_cvt_f16_f32_e32 v0, v60
	v_cvt_f16_f32_e32 v1, v61
	v_cvt_f16_f32_e32 v2, v62
	v_cvt_f16_f32_e32 v48, v63
	v_mfma_f32_16x16x32_f16 v[76:79], v[68:71], v[64:67], v[36:39]
	ds_read2_b64 v[72:75], v80 offset0:64 offset1:68
	ds_read2st64_b64 v[130:133], v216 offset0:20 offset1:25
	ds_read2_b64 v[68:71], v80 offset0:72 offset1:76
	s_nop 0
	s_nop 0
	v_cndmask_b32_e64 v0, 0, v0, s[10:11]
	v_cndmask_b32_e64 v49, 0, v1, s[14:15]
	v_cndmask_b32_e64 v1, 0, v2, s[16:17]
	v_cndmask_b32_e64 v2, 0, v48, s[20:21]
	v_pack_b32_f16 v1, v1, v2
	v_pack_b32_f16 v0, v0, v49
	s_nop 0
	s_nop 0
	s_waitcnt lgkmcnt(1)
	v_mov_b32_e32 v60, v130
	v_mov_b32_e32 v61, v131
	ds_read2_b64 v[126:129], v231 offset1:80
	s_nop 0
	s_nop 0
	v_cvt_f16_f32_e32 v36, v40
	ds_read_b128 v[134:137], v176
	v_cvt_f16_f32_e32 v40, v42
	v_mfma_f32_16x16x16_f16 v[48:51], v[0:1], v[60:61], v[76:79]
	v_cvt_pk_f16_f32 v1, v46, v47
	v_cvt_pk_f16_f32 v0, v44, v45
	v_cvt_f16_f32_e32 v37, v41
	s_nop 0
	s_nop 0
	s_nop 2
	v_cvt_pk_f16_f32 v77, v50, v51
	v_cvt_pk_f16_f32 v76, v48, v49
	v_cndmask_b32_e64 v88, v40, 0, s[18:19]
	v_mfma_f32_16x16x32_f16 v[56:59], v[72:75], v[56:59], 0
	v_cndmask_b32_e64 v36, v36, 0, s[12:13]
	v_cndmask_b32_e64 v37, 0, v37, s[10:11]
	s_nop 0
	v_mfma_f32_16x16x16_f16 v[44:47], v[0:1], v[76:77], 0
	ds_read_b64 v[76:77], v217 offset:5120
	ds_read_b128 v[138:141], v176 offset:64
	s_nop 0
	s_waitcnt lgkmcnt(4)
	v_mfma_f32_16x16x32_f16 v[56:59], v[68:71], v[64:67], v[56:59]
	s_nop 5
	v_cvt_pk_f16_f32 v1, v46, v47
	v_cvt_pk_f16_f32 v0, v44, v45
	s_nop 0
	s_nop 0
	s_nop 0
	s_nop 0
	s_waitcnt lgkmcnt(3)
	v_mov_b32_e32 v80, v126
	v_mov_b32_e32 v81, v127
	ds_read_b64 v[44:45], v218 offset:5120
	ds_read2_b64 v[142:145], v231 offset0:160 offset1:240
	s_nop 0
	s_waitcnt lgkmcnt(4)
	v_pk_mul_f32 v[50:51], v[6:7], v[136:137]
	v_pk_mul_f32 v[48:49], v[4:5], v[134:135]
	ds_read_b128 v[134:137], v176 offset:128
	s_nop 1
	v_mfma_f32_16x16x16_f16 v[48:51], v[80:81], v[0:1], v[48:51]
	v_cvt_f16_f32_e32 v80, v43
	v_cndmask_b32_e64 v89, v80, 0, s[22:23]
	s_nop 0
	s_waitcnt lgkmcnt(4)
	v_mfma_f32_16x16x16_f16 v[40:43], v[76:77], v[60:61], v[48:51]
	s_nop 3
	s_nop 0
	s_nop 0
	ds_read_b64 v[80:81], v219 offset:5120
	v_mov_b32_e32 v76, v128
	v_mov_b32_e32 v77, v129
	s_nop 0
	s_nop 0
	s_waitcnt lgkmcnt(4)
	v_pk_mul_f32 v[50:51], v[10:11], v[140:141]
	v_pk_mul_f32 v[48:49], v[8:9], v[138:139]
	s_nop 0
	ds_read_b128 v[126:129], v176 offset:192
	s_nop 0
	v_mfma_f32_16x16x16_f16 v[48:51], v[76:77], v[0:1], v[48:51]
	s_nop 0
	s_nop 0
	s_waitcnt lgkmcnt(3)
	v_mov_b32_e32 v84, v142
	v_mfma_f32_16x16x16_f16 v[48:51], v[44:45], v[60:61], v[48:51]
	s_nop 0
	s_nop 0
	v_mov_b32_e32 v85, v143
	v_pack_b32_f16 v77, v88, v89
	v_mov_b32_e32 v88, v144
	s_nop 0
	s_waitcnt lgkmcnt(2)
	v_pk_mul_f32 v[46:47], v[14:15], v[136:137]
	v_pk_mul_f32 v[44:45], v[12:13], v[134:135]
	v_mov_b32_e32 v89, v145
	v_pack_b32_f16 v76, v36, v37
	v_mfma_f32_16x16x16_f16 v[44:47], v[84:85], v[0:1], v[44:47]
	ds_read_b64 v[84:85], v220 offset:5120
	v_cndmask_b32_e64 v36, v52, 0, s[12:13]
	v_cvt_f16_f32_e32 v37, v53
	v_cndmask_b32_e64 v37, 0, v37, s[10:11]
	s_nop 0
	s_waitcnt lgkmcnt(2)
	v_mfma_f32_16x16x16_f16 v[44:47], v[80:81], v[60:61], v[44:47]
	s_nop 0
	s_nop 0
	v_pack_b32_f16 v72, v36, v37
	ds_read_b128 v[68:71], v221 offset:9216
	ds_read_b128 v[94:97], v221 offset:9280
	s_nop 0
	s_waitcnt lgkmcnt(3)
	v_pk_mul_f32 v[82:83], v[18:19], v[128:129]
	ds_read_b128 v[64:67], v221 offset:18432
	v_pk_mul_f32 v[80:81], v[16:17], v[126:127]
	s_nop 0
	ds_read_b128 v[98:101], v221 offset:23104
	v_mfma_f32_16x16x16_f16 v[78:81], v[88:89], v[0:1], v[80:83]
	ds_read_b128 v[90:93], v221 offset:18496
	s_nop 1
	v_cvt_f16_f32_e32 v82, v54
	v_cvt_f16_f32_e32 v83, v55
	s_nop 0
	s_waitcnt lgkmcnt(5)
	v_mfma_f32_16x16x16_f16 v[52:55], v[84:85], v[60:61], v[78:81]
	ds_read_b128 v[86:89], v221 offset:13824
	s_nop 1
	v_cndmask_b32_e64 v78, v82, 0, s[18:19]
	v_cndmask_b32_e64 v79, v83, 0, s[22:23]
	v_pack_b32_f16 v73, v78, v79
	s_nop 0
	s_nop 0
	v_add_u32_e32 v80, s71, v153
	v_add_u32_e32 v81, s70, v230
	v_mfma_f32_16x16x16_f16 v[56:59], v[76:77], v[0:1], v[56:59]
	ds_read_b128 v[76:79], v221 offset:23040
	v_subrev_u32_e32 v102, 64, v80
	v_add_u32_e32 v0, 0x7ff, v81
	v_mfma_f32_16x16x16_f16 v[58:61], v[72:73], v[60:61], v[56:59]
	v_cndmask_b32_e64 v0, v0, v102, s[2:3]
	v_add_u32_e32 v0, v0, v151
	v_mad_i64_i32 v[0:1], s[26:27], v0, s91, v[122:123]
	s_nop 0
	s_waitcnt lgkmcnt(4)
	v_mfma_f32_16x16x32_f16 v[82:85], v[68:71], v[64:67], 0
	s_nop 2
	v_cvt_f16_f32_e32 v2, v58
	v_cvt_f16_f32_e32 v60, v60
	ds_read_b128 v[126:129], v221 offset:13888
	global_store_short v[0:1], v2, off
	v_subrev_u32_e32 v0, 63, v80
	v_xad_u32 v1, v102, -2, v170
	v_cvt_f16_f32_e32 v2, v59
	s_nop 0
	v_mfma_f32_16x16x32_f16 v[72:75], v[64:67], v[68:71], 0
	v_cndmask_b32_e64 v0, v1, v0, s[2:3]
	v_add_u32_e32 v0, v0, v151
	v_mad_i64_i32 v[0:1], s[26:27], v0, s91, v[122:123]
	s_nop 0
	s_waitcnt lgkmcnt(2)
	v_mfma_f32_16x16x32_f16 v[62:65], v[64:67], v[86:89], 0
	global_store_short v[0:1], v2, off
	v_subrev_u32_e32 v0, 62, v80
	v_xad_u32 v1, v102, -3, v170
	v_mfma_f32_16x16x32_f16 v[82:85], v[94:97], v[90:93], v[82:85]
	v_cndmask_b32_e64 v36, v1, v0, s[2:3]
	v_add_u32_e32 v36, v36, v151
	s_nop 0
	s_waitcnt lgkmcnt(1)
	v_mfma_f32_16x16x32_f16 v[68:71], v[76:79], v[68:71], 0
	v_mfma_f32_16x16x32_f16 v[86:89], v[76:79], v[86:89], 0
	s_nop 2
	v_cvt_f16_f32_e32 v1, v82
	v_cvt_f16_f32_e32 v2, v83
	v_cvt_f16_f32_e32 v66, v85
	v_mfma_f32_16x16x32_f16 v[72:75], v[90:93], v[94:97], v[72:75]
	s_nop 0
	v_cndmask_b32_e64 v66, 0, v66, s[22:23]
	s_nop 0
	s_waitcnt lgkmcnt(0)
	v_mfma_f32_16x16x32_f16 v[76:79], v[90:93], v[126:129], v[62:65]
	s_nop 0
	s_nop 2
	v_cndmask_b32_e64 v0, 0, v72, s[10:11]
	v_cndmask_b32_e64 v37, 0, v73, s[14:15]
	v_cvt_f16_f32_e32 v63, v84
	v_mfma_f32_16x16x32_f16 v[94:97], v[98:101], v[94:97], v[68:71]
	v_cndmask_b32_e64 v64, 0, v74, s[16:17]
	v_cndmask_b32_e64 v65, 0, v75, s[20:21]
	v_cndmask_b32_e64 v63, 0, v63, s[18:19]
	v_cndmask_b32_e64 v68, 0, v1, s[12:13]
	v_cndmask_b32_e64 v69, v2, 0, s[10:11]
	v_add_f32_e32 v62, v211, v0
	v_cvt_pk_f16_f32 v1, v64, v65
	v_cvt_pk_f16_f32 v0, v0, v37
	s_nop 0
	v_pack_b32_f16 v67, v63, v66
	v_pack_b32_f16 v66, v68, v69
	s_nop 0
	s_nop 0
	v_add_f32_e32 v63, v212, v37
	v_add_f32_e32 v64, v213, v64
	v_mfma_f32_16x16x16_f16 v[70:73], v[0:1], v[66:67], 0
	v_add_f32_e32 v65, v214, v65
	v_cvt_pk_f16_f32 v83, v64, v65
	v_cvt_pk_f16_f32 v82, v62, v63
	v_mfma_f32_16x16x16_f16 v[66:69], v[66:67], v[0:1], 0
	s_nop 0
	s_nop 2
	v_cvt_pk_f16_f32 v0, v70, v71
	s_nop 0
	s_nop 0
	v_cvt_pk_f16_f32 v1, v72, v73
	v_cvt_pk_f16_f32 v69, v68, v69
	v_cvt_pk_f16_f32 v68, v66, v67
	v_mfma_f32_16x16x16_f16 v[62:65], v[0:1], v[82:83], v[62:65]
	v_mad_i64_i32 v[36:37], s[26:27], v36, s91, v[122:123]
	global_store_short v[36:37], v60, off
	v_mfma_f32_16x16x16_f16 v[72:75], v[68:69], v[0:1], 0
	v_cvt_f16_f32_e32 v82, v61
	v_subrev_u32_e32 v36, 61, v80
	v_xad_u32 v37, v102, -4, v170
	v_mfma_f32_16x16x16_f16 v[66:69], v[0:1], v[68:69], 0
	s_nop 0
	v_cvt_pk_f16_f32 v71, v64, v65
	s_nop 1
	v_cvt_pk_f16_f32 v1, v74, v75
	v_cvt_pk_f16_f32 v0, v72, v73
	ds_read2_b64 v[134:137], v222 offset1:4
	v_mfma_f32_16x16x32_f16 v[56:59], v[98:101], v[126:129], v[86:89]
	v_cvt_pk_f16_f32 v70, v62, v63
	s_nop 0
	s_nop 0
	v_cvt_pk_f16_f32 v85, v68, v69
	ds_read2_b64 v[126:129], v222 offset0:8 offset1:12
	v_cvt_pk_f16_f32 v84, v66, v67
	s_nop 0
	s_nop 0
	v_mfma_f32_16x16x16_f16 v[88:91], v[0:1], v[70:71], v[62:65]
	s_nop 0
	s_nop 0
	v_cndmask_b32_e64 v36, v37, v36, s[2:3]
	v_mfma_f32_16x16x16_f16 v[60:63], v[84:85], v[0:1], 0
	v_add_u32_e32 v83, v36, v151
	s_nop 2
	v_cvt_pk_f16_f32 v1, v90, v91
	v_cvt_pk_f16_f32 v0, v88, v89
	v_cvt_pk_f16_f32 v67, v54, v55
	v_cvt_pk_f16_f32 v66, v52, v53
	v_cvt_pk_f16_f32 v85, v62, v63
	v_cvt_pk_f16_f32 v84, v60, v61
	v_cvt_pk_f16_f32 v63, v50, v51
	v_cvt_pk_f16_f32 v62, v48, v49
	v_cvt_pk_f16_f32 v61, v42, v43
	v_cvt_pk_f16_f32 v60, v40, v41
	v_cvt_pk_f16_f32 v65, v46, v47
	v_cvt_pk_f16_f32 v64, v44, v45
	s_nop 0
	s_waitcnt lgkmcnt(1)
	v_mfma_f32_16x16x32_f16 v[68:71], v[134:137], v[60:63], 0
	v_add_u32_e32 v36, 0x1000, v222
	s_nop 0
	v_cvt_f16_f32_e32 v76, v76
	s_nop 0
	s_waitcnt lgkmcnt(0)
	v_mfma_f32_16x16x32_f16 v[98:101], v[126:129], v[64:67], v[68:71]
	ds_read2_b64 v[72:75], v36 offset0:64 offset1:68
	s_nop 1
	ds_read2_b64 v[68:71], v36 offset0:72 offset1:76
	v_cvt_f16_f32_e32 v36, v97
	v_cvt_f16_f32_e32 v97, v77
	v_mfma_f32_16x16x16_f16 v[84:87], v[84:85], v[0:1], v[88:91]
	v_cvt_f16_f32_e32 v0, v94
	v_cvt_f16_f32_e32 v1, v95
	v_cvt_f16_f32_e32 v2, v96
	v_cndmask_b32_e64 v96, v76, 0, s[12:13]
	v_cndmask_b32_e64 v0, 0, v0, s[10:11]
	v_cndmask_b32_e64 v37, 0, v1, s[14:15]
	v_cndmask_b32_e64 v1, 0, v2, s[16:17]
	v_cndmask_b32_e64 v2, 0, v36, s[20:21]
	v_pack_b32_f16 v1, v1, v2
	v_pack_b32_f16 v0, v0, v37
	s_nop 0
	v_mov_b32_e32 v36, v132
	v_mov_b32_e32 v37, v133
	s_nop 0
	s_nop 0
	v_mov_b32_e32 v94, v3
	v_mov_b32_e32 v95, v3
	v_mfma_f32_16x16x16_f16 v[88:91], v[0:1], v[36:37], v[98:101]
	v_cvt_pk_f16_f32 v1, v86, v87
	v_cvt_pk_f16_f32 v0, v84, v85
	v_cvt_f16_f32_e32 v56, v56
	v_cvt_f16_f32_e32 v98, v78
	v_cvt_f16_f32_e32 v99, v79
	s_nop 2
	v_cvt_pk_f16_f32 v91, v90, v91
	v_cvt_pk_f16_f32 v90, v88, v89
	v_cndmask_b32_e64 v97, 0, v97, s[10:11]
	v_cndmask_b32_e64 v98, v98, 0, s[18:19]
	v_mfma_f32_16x16x16_f16 v[84:87], v[0:1], v[90:91], 0
	v_add_u32_e32 v2, 0x800, v231
	ds_read2_b64 v[126:129], v2 offset0:64 offset1:144
	ds_read_b128 v[76:79], v176 offset:256
	v_mov_b32_e32 v90, v3
	v_mov_b32_e32 v91, v3
	v_cndmask_b32_e64 v99, v99, 0, s[22:23]
	ds_read_b64 v[88:89], v223 offset:5120
	ds_read_b128 v[130:133], v176 offset:320
	s_nop 3
	v_cvt_pk_f16_f32 v1, v86, v87
	v_cvt_pk_f16_f32 v0, v84, v85
	s_nop 0
	s_nop 0
	s_nop 0
	s_nop 0
	s_nop 0
	s_waitcnt lgkmcnt(3)
	v_mov_b32_e32 v92, v126
	v_mov_b32_e32 v93, v127
	ds_read_b64 v[84:85], v224 offset:5120
	s_nop 0
	s_waitcnt lgkmcnt(3)
	v_pk_mul_f32 v[42:43], v[42:43], v[78:79]
	v_pk_mul_f32 v[40:41], v[40:41], v[76:77]
	s_nop 0
	s_nop 0
	v_mfma_f32_16x16x16_f16 v[40:43], v[92:93], v[0:1], v[40:43]
	s_nop 0
	s_waitcnt lgkmcnt(1)
	v_pk_mul_f32 v[48:49], v[48:49], v[130:131]
	v_add_u32_e32 v76, 0xc00, v231
	ds_read2_b64 v[134:137], v76 offset0:96 offset1:176
	ds_read_b128 v[138:141], v176 offset:384
	v_mfma_f32_16x16x16_f16 v[40:43], v[88:89], v[36:37], v[40:43]
	v_mov_b32_e32 v88, v128
	v_mov_b32_e32 v89, v129
	v_pk_mul_f32 v[50:51], v[50:51], v[132:133]
	s_nop 0
	s_nop 0
	s_nop 0
	v_mfma_f32_16x16x16_f16 v[48:51], v[88:89], v[0:1], v[48:51]
	ds_read_b64 v[88:89], v225 offset:5120
	s_nop 0
	s_waitcnt lgkmcnt(2)
	v_mov_b32_e32 v92, v134
	v_mfma_f32_16x16x16_f16 v[48:51], v[84:85], v[36:37], v[48:51]
	s_nop 0
	s_nop 0
	v_mov_b32_e32 v93, v135
	v_pack_b32_f16 v76, v96, v97
	v_cndmask_b32_e64 v96, v56, 0, s[12:13]
	s_nop 0
	s_waitcnt lgkmcnt(1)
	v_pk_mul_f32 v[46:47], v[46:47], v[140:141]
	v_pk_mul_f32 v[44:45], v[44:45], v[138:139]
	ds_read_b128 v[84:87], v176 offset:448
	v_cvt_f16_f32_e32 v56, v57
	v_cvt_f16_f32_e32 v57, v58
	v_mfma_f32_16x16x16_f16 v[44:47], v[92:93], v[0:1], v[44:47]
	v_cvt_f16_f32_e32 v58, v59
	v_mov_b32_e32 v92, v136
	v_mov_b32_e32 v93, v137
	s_nop 0
	s_waitcnt lgkmcnt(1)
	v_mfma_f32_16x16x16_f16 v[44:47], v[88:89], v[36:37], v[44:47]
	ds_read_b64 v[88:89], v226 offset:5120
	s_nop 0
	s_nop 0
	v_cndmask_b32_e64 v78, v57, 0, s[18:19]
	v_cndmask_b32_e64 v79, v58, 0, s[22:23]
	v_pack_b32_f16 v77, v98, v99
	s_nop 0
	s_waitcnt lgkmcnt(1)
	v_pk_mul_f32 v[52:53], v[52:53], v[84:85]
	v_cndmask_b32_e64 v84, 0, v56, s[10:11]
	v_mfma_f32_16x16x32_f16 v[56:59], v[72:75], v[60:63], 0
	v_pack_b32_f16 v61, v78, v79
	v_mov_b32_e32 v78, v3
	v_mov_b32_e32 v79, v3
	v_mfma_f32_16x16x32_f16 v[56:59], v[68:71], v[64:67], v[56:59]
	v_mul_f32_e64 v54, v54, v86
	v_mul_f32_e64 v55, v55, v87
	v_pack_b32_f16 v60, v96, v84
	v_mov_b32_e32 v62, v3
	v_mov_b32_e32 v63, v3
	v_mfma_f32_16x16x16_f16 v[52:55], v[92:93], v[0:1], v[52:55]
	v_mfma_f32_16x16x16_f16 v[56:59], v[76:77], v[0:1], v[56:59]
	v_mad_i64_i32 v[0:1], s[26:27], v83, s91, v[122:123]
	global_store_short v[0:1], v82, off
	s_nop 0
	s_waitcnt lgkmcnt(0)
	v_mfma_f32_16x16x16_f16 v[52:55], v[88:89], v[36:37], v[52:55]
	v_subrev_u32_e32 v0, 48, v80
	v_add_u32_e32 v1, 0x7ef, v81
	v_cndmask_b32_e64 v0, v1, v0, s[2:3]
	v_mfma_f32_16x16x16_f16 v[36:39], v[60:61], v[36:37], v[56:59]
	v_add_u32_e32 v0, v0, v151
	v_mad_i64_i32 v[0:1], s[26:27], v0, s91, v[122:123]
	s_nop 5
	v_cvt_f16_f32_e32 v2, v36
	global_store_short v[0:1], v2, off
	v_subrev_u32_e32 v0, 47, v80
	v_add_u32_e32 v1, 0x7ee, v81
	v_cvt_f16_f32_e32 v2, v37
	v_cndmask_b32_e64 v0, v1, v0, s[2:3]
	v_add_u32_e32 v0, v0, v151
	v_mad_i64_i32 v[0:1], s[26:27], v0, s91, v[122:123]
	global_store_short v[0:1], v2, off
	v_subrev_u32_e32 v0, 46, v80
	v_add_u32_e32 v1, 0x7ed, v81
	v_cvt_f16_f32_e32 v2, v38
	v_cndmask_b32_e64 v0, v1, v0, s[2:3]
	v_add_u32_e32 v0, v0, v151
	v_mad_i64_i32 v[0:1], s[26:27], v0, s91, v[122:123]
	global_store_short v[0:1], v2, off
	v_subrev_u32_e32 v0, 45, v80
	v_add_u32_e32 v1, 0x7ec, v81
	v_cndmask_b32_e64 v0, v1, v0, s[2:3]
	v_cvt_f16_f32_e32 v2, v39
	v_add_u32_e32 v0, v0, v151
	v_mad_i64_i32 v[0:1], s[26:27], v0, s91, v[122:123]
	s_mov_b64 s[26:27], 0
	global_store_short v[0:1], v2, off

.LBB0_935:
	s_or_b64 exec, exec, s[28:29]
	s_waitcnt lgkmcnt(0)
	s_barrier
	ds_read_b128 v[40:43], v216 offset:9216
	ds_read_b128 v[48:51], v216 offset:18496
	ds_read_b128 v[56:59], v216 offset:9280
	ds_read_b128 v[60:63], v216 offset:23040
	ds_read_b128 v[36:39], v216 offset:18432
	s_nop 0
	s_nop 0
	s_nop 0
	ds_read_b128 v[64:67], v216 offset:13824
	s_waitcnt lgkmcnt(1)
	v_mfma_f32_16x16x32_f16 v[52:55], v[40:43], v[36:39], 0
	s_nop 0
	s_nop 0
	s_nop 0
	ds_read_b128 v[68:71], v216 offset:13888
	ds_read_b128 v[72:75], v216 offset:23104
	v_add_u32_e32 v80, 0x1000, v222
	s_nop 0
	v_mfma_f32_16x16x32_f16 v[52:55], v[56:59], v[48:51], v[52:55]
	s_nop 0
	s_nop 0
	s_nop 0
	v_mfma_f32_16x16x32_f16 v[44:47], v[36:39], v[40:43], 0
	s_nop 3
	v_cvt_f16_f32_e32 v0, v52
	v_cvt_f16_f32_e32 v1, v54
	v_cvt_f16_f32_e32 v2, v55
	v_mfma_f32_16x16x32_f16 v[44:47], v[48:51], v[56:59], v[44:47]
	v_cndmask_b32_e64 v79, 0, v0, s[12:13]
	v_cvt_f16_f32_e32 v0, v53
	v_cndmask_b32_e64 v54, 0, v1, s[18:19]
	s_nop 0
	v_mfma_f32_16x16x32_f16 v[40:43], v[60:63], v[40:43], 0
	v_cndmask_b32_e64 v55, 0, v2, s[22:23]
	s_nop 1
	v_cndmask_b32_e64 v76, 0, v44, s[10:11]
	v_cndmask_b32_e64 v77, 0, v45, s[14:15]
	s_nop 0
	s_waitcnt lgkmcnt(2)
	v_mfma_f32_16x16x32_f16 v[36:39], v[36:39], v[64:67], 0
	v_cndmask_b32_e64 v52, 0, v46, s[16:17]
	v_cndmask_b32_e64 v78, 0, v47, s[20:21]
	v_cndmask_b32_e64 v53, v0, 0, s[10:11]
	v_mfma_f32_16x16x32_f16 v[44:47], v[60:63], v[64:67], 0
	v_cvt_pk_f16_f32 v1, v52, v78
	v_cvt_pk_f16_f32 v0, v76, v77
	s_nop 0
	s_nop 0
	s_waitcnt lgkmcnt(0)
	v_mfma_f32_16x16x32_f16 v[60:63], v[72:75], v[56:59], v[40:43]
	v_add_f32_e32 v56, v217, v76
	v_add_f32_e32 v57, v219, v77
	v_add_f32_e32 v58, v220, v52
	v_mfma_f32_16x16x32_f16 v[40:43], v[48:51], v[68:71], v[36:39]
	v_add_f32_e32 v59, v221, v78
	v_cvt_pk_f16_f32 v67, v26, v27
	v_cvt_pk_f16_f32 v66, v24, v25
	v_pack_b32_f16 v37, v54, v55
	v_pack_b32_f16 v36, v79, v53
	s_nop 0
	s_nop 0
	v_mfma_f32_16x16x32_f16 v[52:55], v[72:75], v[68:71], v[44:47]
	ds_read2_b64 v[68:71], v222 offset0:8 offset1:12
	v_cvt_pk_f16_f32 v65, v30, v31
	v_cvt_pk_f16_f32 v64, v28, v29
	v_mfma_f32_16x16x16_f16 v[48:51], v[0:1], v[36:37], 0
	v_cvt_pk_f16_f32 v45, v58, v59
	v_cvt_pk_f16_f32 v44, v56, v57
	s_nop 0
	v_mfma_f32_16x16x16_f16 v[36:39], v[36:37], v[0:1], 0
	s_nop 0
	s_nop 2
	v_cvt_pk_f16_f32 v1, v50, v51
	v_cvt_pk_f16_f32 v0, v48, v49
	s_nop 0
	s_nop 0
	v_cvt_pk_f16_f32 v49, v38, v39
	v_cvt_pk_f16_f32 v48, v36, v37
	v_mfma_f32_16x16x16_f16 v[44:47], v[0:1], v[44:45], v[56:59]
	s_nop 0
	s_nop 0
	s_nop 0
	v_mfma_f32_16x16x16_f16 v[36:39], v[48:49], v[0:1], 0
	ds_read2_b64 v[128:131], v222 offset1:4
	v_cvt_pk_f16_f32 v59, v34, v35
	v_cvt_pk_f16_f32 v58, v32, v33
	v_cvt_pk_f16_f32 v57, v22, v23
	v_mfma_f32_16x16x16_f16 v[48:51], v[0:1], v[48:49], 0
	v_cvt_pk_f16_f32 v56, v20, v21
	s_nop 2
	v_cvt_pk_f16_f32 v1, v38, v39
	v_cvt_pk_f16_f32 v0, v36, v37
	v_cvt_pk_f16_f32 v37, v46, v47
	v_cvt_pk_f16_f32 v36, v44, v45
	s_nop 0
	s_nop 0
	v_cvt_f16_f32_e32 v52, v52
	s_add_i32 s27, s26, 1
	v_mfma_f32_16x16x16_f16 v[44:47], v[0:1], v[36:37], v[44:47]
	v_cvt_pk_f16_f32 v37, v50, v51
	v_cvt_pk_f16_f32 v36, v48, v49
	s_nop 0
	s_nop 0
	v_mfma_f32_16x16x16_f16 v[36:39], v[36:37], v[0:1], 0
	s_nop 2
	v_cvt_pk_f16_f32 v1, v46, v47
	v_cvt_pk_f16_f32 v0, v44, v45
	s_nop 2
	v_cvt_pk_f16_f32 v49, v38, v39
	v_cvt_pk_f16_f32 v48, v36, v37
	s_nop 0
	s_nop 0
	s_waitcnt lgkmcnt(0)
	v_mfma_f32_16x16x32_f16 v[36:39], v[128:131], v[56:59], 0
	v_mfma_f32_16x16x16_f16 v[44:47], v[48:49], v[0:1], v[44:47]
	v_cvt_f16_f32_e32 v0, v60
	v_cvt_f16_f32_e32 v1, v61
	v_cvt_f16_f32_e32 v2, v62
	v_cvt_f16_f32_e32 v48, v63
	v_mfma_f32_16x16x32_f16 v[76:79], v[68:71], v[64:67], v[36:39]
	ds_read2_b64 v[72:75], v80 offset0:64 offset1:68
	ds_read2st64_b64 v[132:135], v223 offset0:20 offset1:25
	ds_read2_b64 v[68:71], v80 offset0:72 offset1:76
	s_nop 0
	s_nop 0
	v_cndmask_b32_e64 v0, 0, v0, s[10:11]
	v_cndmask_b32_e64 v49, 0, v1, s[14:15]
	v_cndmask_b32_e64 v1, 0, v2, s[16:17]
	v_cndmask_b32_e64 v2, 0, v48, s[20:21]
	v_pack_b32_f16 v1, v1, v2
	v_pack_b32_f16 v0, v0, v49
	s_nop 0
	s_nop 0
	s_waitcnt lgkmcnt(1)
	v_mov_b32_e32 v60, v132
	v_mov_b32_e32 v61, v133
	ds_read2_b64 v[128:131], v240 offset1:80
	s_nop 0
	s_nop 0
	v_cvt_f16_f32_e32 v36, v40
	ds_read_b128 v[136:139], v182
	v_cvt_f16_f32_e32 v40, v42
	v_mfma_f32_16x16x16_f16 v[48:51], v[0:1], v[60:61], v[76:79]
	v_cvt_pk_f16_f32 v1, v46, v47
	v_cvt_pk_f16_f32 v0, v44, v45
	v_cvt_f16_f32_e32 v37, v41
	s_nop 0
	s_nop 0
	s_nop 2
	v_cvt_pk_f16_f32 v77, v50, v51
	v_cvt_pk_f16_f32 v76, v48, v49
	v_cndmask_b32_e64 v88, v40, 0, s[18:19]
	v_mfma_f32_16x16x32_f16 v[56:59], v[72:75], v[56:59], 0
	v_cndmask_b32_e64 v36, v36, 0, s[12:13]
	v_cndmask_b32_e64 v37, 0, v37, s[10:11]
	s_nop 0
	v_mfma_f32_16x16x16_f16 v[44:47], v[0:1], v[76:77], 0
	ds_read_b64 v[76:77], v224 offset:5120
	ds_read_b128 v[140:143], v182 offset:64
	s_nop 0
	s_waitcnt lgkmcnt(4)
	v_mfma_f32_16x16x32_f16 v[56:59], v[68:71], v[64:67], v[56:59]
	s_nop 5
	v_cvt_pk_f16_f32 v1, v46, v47
	v_cvt_pk_f16_f32 v0, v44, v45
	s_nop 0
	s_nop 0
	s_nop 0
	s_nop 0
	s_waitcnt lgkmcnt(3)
	v_mov_b32_e32 v80, v128
	v_mov_b32_e32 v81, v129
	ds_read_b64 v[44:45], v225 offset:5120
	ds_read2_b64 v[144:147], v240 offset0:160 offset1:240
	s_nop 0
	s_waitcnt lgkmcnt(4)
	v_pk_mul_f32 v[50:51], v[22:23], v[138:139]
	v_pk_mul_f32 v[48:49], v[20:21], v[136:137]
	ds_read_b128 v[136:139], v182 offset:128
	s_nop 1
	v_mfma_f32_16x16x16_f16 v[48:51], v[80:81], v[0:1], v[48:51]
	v_cvt_f16_f32_e32 v80, v43
	v_cndmask_b32_e64 v89, v80, 0, s[22:23]
	s_nop 0
	s_waitcnt lgkmcnt(4)
	v_mfma_f32_16x16x16_f16 v[40:43], v[76:77], v[60:61], v[48:51]
	s_nop 3
	s_nop 0
	s_nop 0
	ds_read_b64 v[80:81], v226 offset:5120
	v_mov_b32_e32 v76, v130
	v_mov_b32_e32 v77, v131
	s_nop 0
	s_nop 0
	s_waitcnt lgkmcnt(4)
	v_pk_mul_f32 v[50:51], v[34:35], v[142:143]
	v_pk_mul_f32 v[48:49], v[32:33], v[140:141]
	s_nop 0
	ds_read_b128 v[128:131], v182 offset:192
	s_nop 0
	v_mfma_f32_16x16x16_f16 v[48:51], v[76:77], v[0:1], v[48:51]
	s_nop 0
	s_nop 0
	s_waitcnt lgkmcnt(3)
	v_mov_b32_e32 v84, v144
	v_mfma_f32_16x16x16_f16 v[48:51], v[44:45], v[60:61], v[48:51]
	s_nop 0
	s_nop 0
	v_mov_b32_e32 v85, v145
	v_pack_b32_f16 v77, v88, v89
	v_mov_b32_e32 v88, v146
	s_nop 0
	s_waitcnt lgkmcnt(2)
	v_pk_mul_f32 v[46:47], v[30:31], v[138:139]
	v_pk_mul_f32 v[44:45], v[28:29], v[136:137]
	v_mov_b32_e32 v89, v147
	v_pack_b32_f16 v76, v36, v37
	v_mfma_f32_16x16x16_f16 v[44:47], v[84:85], v[0:1], v[44:47]
	ds_read_b64 v[84:85], v227 offset:5120
	v_cndmask_b32_e64 v36, v52, 0, s[12:13]
	v_cvt_f16_f32_e32 v37, v53
	v_cndmask_b32_e64 v37, 0, v37, s[10:11]
	s_nop 0
	s_waitcnt lgkmcnt(2)
	v_mfma_f32_16x16x16_f16 v[44:47], v[80:81], v[60:61], v[44:47]
	s_nop 0
	s_nop 0
	v_pack_b32_f16 v72, v36, v37
	ds_read_b128 v[68:71], v228 offset:9216
	ds_read_b128 v[94:97], v228 offset:9280
	s_nop 0
	s_waitcnt lgkmcnt(3)
	v_pk_mul_f32 v[82:83], v[26:27], v[130:131]
	ds_read_b128 v[64:67], v228 offset:18432
	v_pk_mul_f32 v[80:81], v[24:25], v[128:129]
	s_nop 0
	ds_read_b128 v[98:101], v228 offset:23104
	v_mfma_f32_16x16x16_f16 v[78:81], v[88:89], v[0:1], v[80:83]
	ds_read_b128 v[90:93], v228 offset:18496
	s_nop 1
	v_cvt_f16_f32_e32 v82, v54
	v_cvt_f16_f32_e32 v83, v55
	s_nop 0
	s_waitcnt lgkmcnt(5)
	v_mfma_f32_16x16x16_f16 v[52:55], v[84:85], v[60:61], v[78:81]
	ds_read_b128 v[86:89], v228 offset:13824
	s_nop 1
	v_cndmask_b32_e64 v78, v82, 0, s[18:19]
	v_cndmask_b32_e64 v79, v83, 0, s[22:23]
	v_pack_b32_f16 v73, v78, v79
	s_nop 0
	s_nop 0
	v_add_u32_e32 v80, s77, v122
	v_add_u32_e32 v81, s76, v237
	v_mfma_f32_16x16x16_f16 v[56:59], v[76:77], v[0:1], v[56:59]
	ds_read_b128 v[76:79], v228 offset:23040
	v_subrev_u32_e32 v102, 64, v80
	v_add_u32_e32 v0, 0xff, v81
	v_mfma_f32_16x16x16_f16 v[58:61], v[72:73], v[60:61], v[56:59]
	v_cndmask_b32_e64 v0, v0, v102, s[2:3]
	v_add_u32_e32 v0, v0, v175
	v_mad_i64_i32 v[0:1], s[28:29], v0, s88, v[126:127]
	s_nop 0
	s_waitcnt lgkmcnt(4)
	v_mfma_f32_16x16x32_f16 v[82:85], v[68:71], v[64:67], 0
	s_nop 2
	v_cvt_f16_f32_e32 v2, v58
	v_cvt_f16_f32_e32 v60, v60
	ds_read_b128 v[128:131], v228 offset:13888
	global_store_short v[0:1], v2, off
	v_subrev_u32_e32 v0, 63, v80
	v_xad_u32 v1, v102, -2, v168
	v_cvt_f16_f32_e32 v2, v59
	s_nop 0
	v_mfma_f32_16x16x32_f16 v[72:75], v[64:67], v[68:71], 0
	v_cndmask_b32_e64 v0, v1, v0, s[2:3]
	v_add_u32_e32 v0, v0, v175
	v_mad_i64_i32 v[0:1], s[28:29], v0, s88, v[126:127]
	s_nop 0
	s_waitcnt lgkmcnt(2)
	v_mfma_f32_16x16x32_f16 v[62:65], v[64:67], v[86:89], 0
	global_store_short v[0:1], v2, off
	v_subrev_u32_e32 v0, 62, v80
	v_xad_u32 v1, v102, -3, v168
	v_mfma_f32_16x16x32_f16 v[82:85], v[94:97], v[90:93], v[82:85]
	v_cndmask_b32_e64 v36, v1, v0, s[2:3]
	v_add_u32_e32 v36, v36, v175
	s_nop 0
	s_waitcnt lgkmcnt(1)
	v_mfma_f32_16x16x32_f16 v[68:71], v[76:79], v[68:71], 0
	v_mfma_f32_16x16x32_f16 v[86:89], v[76:79], v[86:89], 0
	s_nop 2
	v_cvt_f16_f32_e32 v1, v82
	v_cvt_f16_f32_e32 v2, v83
	v_cvt_f16_f32_e32 v66, v85
	v_mfma_f32_16x16x32_f16 v[72:75], v[90:93], v[94:97], v[72:75]
	s_nop 0
	v_cndmask_b32_e64 v66, 0, v66, s[22:23]
	s_nop 0
	s_waitcnt lgkmcnt(0)
	v_mfma_f32_16x16x32_f16 v[76:79], v[90:93], v[128:131], v[62:65]
	s_nop 0
	s_nop 2
	v_cndmask_b32_e64 v0, 0, v72, s[10:11]
	v_cndmask_b32_e64 v37, 0, v73, s[14:15]
	v_cvt_f16_f32_e32 v63, v84
	v_mfma_f32_16x16x32_f16 v[94:97], v[98:101], v[94:97], v[68:71]
	v_cndmask_b32_e64 v64, 0, v74, s[16:17]
	v_cndmask_b32_e64 v65, 0, v75, s[20:21]
	v_cndmask_b32_e64 v63, 0, v63, s[18:19]
	v_cndmask_b32_e64 v68, 0, v1, s[12:13]
	v_cndmask_b32_e64 v69, v2, 0, s[10:11]
	v_add_f32_e32 v62, v217, v0
	v_cvt_pk_f16_f32 v1, v64, v65
	v_cvt_pk_f16_f32 v0, v0, v37
	s_nop 0
	v_pack_b32_f16 v67, v63, v66
	v_pack_b32_f16 v66, v68, v69
	s_nop 0
	s_nop 0
	v_add_f32_e32 v63, v219, v37
	v_add_f32_e32 v64, v220, v64
	v_mfma_f32_16x16x16_f16 v[70:73], v[0:1], v[66:67], 0
	v_add_f32_e32 v65, v221, v65
	v_cvt_pk_f16_f32 v83, v64, v65
	v_cvt_pk_f16_f32 v82, v62, v63
	v_mfma_f32_16x16x16_f16 v[66:69], v[66:67], v[0:1], 0
	s_nop 0
	s_nop 2
	v_cvt_pk_f16_f32 v0, v70, v71
	s_nop 0
	s_nop 0
	v_cvt_pk_f16_f32 v1, v72, v73
	v_cvt_pk_f16_f32 v69, v68, v69
	v_cvt_pk_f16_f32 v68, v66, v67
	v_mfma_f32_16x16x16_f16 v[62:65], v[0:1], v[82:83], v[62:65]
	v_mad_i64_i32 v[36:37], s[28:29], v36, s88, v[126:127]
	global_store_short v[36:37], v60, off
	v_mfma_f32_16x16x16_f16 v[72:75], v[68:69], v[0:1], 0
	v_cvt_f16_f32_e32 v82, v61
	v_subrev_u32_e32 v36, 61, v80
	v_xad_u32 v37, v102, -4, v168
	v_mfma_f32_16x16x16_f16 v[66:69], v[0:1], v[68:69], 0
	s_nop 0
	v_cvt_pk_f16_f32 v71, v64, v65
	s_nop 1
	v_cvt_pk_f16_f32 v1, v74, v75
	v_cvt_pk_f16_f32 v0, v72, v73
	ds_read2_b64 v[136:139], v229 offset1:4
	v_mfma_f32_16x16x32_f16 v[56:59], v[98:101], v[128:131], v[86:89]
	v_cvt_pk_f16_f32 v70, v62, v63
	s_nop 0
	s_nop 0
	v_cvt_pk_f16_f32 v85, v68, v69
	ds_read2_b64 v[128:131], v229 offset0:8 offset1:12
	v_cvt_pk_f16_f32 v84, v66, v67
	s_nop 0
	s_nop 0
	v_mfma_f32_16x16x16_f16 v[88:91], v[0:1], v[70:71], v[62:65]
	s_nop 0
	s_nop 0
	v_cndmask_b32_e64 v36, v37, v36, s[2:3]
	v_mfma_f32_16x16x16_f16 v[60:63], v[84:85], v[0:1], 0
	v_add_u32_e32 v83, v36, v175
	s_nop 2
	v_cvt_pk_f16_f32 v1, v90, v91
	v_cvt_pk_f16_f32 v0, v88, v89
	v_cvt_pk_f16_f32 v67, v54, v55
	v_cvt_pk_f16_f32 v66, v52, v53
	v_cvt_pk_f16_f32 v85, v62, v63
	v_cvt_pk_f16_f32 v84, v60, v61
	v_cvt_pk_f16_f32 v63, v50, v51
	v_cvt_pk_f16_f32 v62, v48, v49
	v_cvt_pk_f16_f32 v61, v42, v43
	v_cvt_pk_f16_f32 v60, v40, v41
	v_cvt_pk_f16_f32 v65, v46, v47
	v_cvt_pk_f16_f32 v64, v44, v45
	s_nop 0
	s_waitcnt lgkmcnt(1)
	v_mfma_f32_16x16x32_f16 v[68:71], v[136:139], v[60:63], 0
	v_add_u32_e32 v36, 0x1000, v229
	s_nop 0
	v_cvt_f16_f32_e32 v76, v76
	s_nop 0
	s_waitcnt lgkmcnt(0)
	v_mfma_f32_16x16x32_f16 v[98:101], v[128:131], v[64:67], v[68:71]
	ds_read2_b64 v[72:75], v36 offset0:64 offset1:68
	s_nop 1
	ds_read2_b64 v[68:71], v36 offset0:72 offset1:76
	v_cvt_f16_f32_e32 v36, v97
	v_cvt_f16_f32_e32 v97, v77
	v_mfma_f32_16x16x16_f16 v[84:87], v[84:85], v[0:1], v[88:91]
	v_cvt_f16_f32_e32 v0, v94
	v_cvt_f16_f32_e32 v1, v95
	v_cvt_f16_f32_e32 v2, v96
	v_cndmask_b32_e64 v96, v76, 0, s[12:13]
	v_cndmask_b32_e64 v0, 0, v0, s[10:11]
	v_cndmask_b32_e64 v37, 0, v1, s[14:15]
	v_cndmask_b32_e64 v1, 0, v2, s[16:17]
	v_cndmask_b32_e64 v2, 0, v36, s[20:21]
	v_pack_b32_f16 v1, v1, v2
	v_pack_b32_f16 v0, v0, v37
	s_nop 0
	v_mov_b32_e32 v36, v134
	v_mov_b32_e32 v37, v135
	s_nop 0
	s_nop 0
	v_mov_b32_e32 v94, v3
	v_mov_b32_e32 v95, v3
	v_mfma_f32_16x16x16_f16 v[88:91], v[0:1], v[36:37], v[98:101]
	v_cvt_pk_f16_f32 v1, v86, v87
	v_cvt_pk_f16_f32 v0, v84, v85
	v_cvt_f16_f32_e32 v56, v56
	v_cvt_f16_f32_e32 v98, v78
	v_cvt_f16_f32_e32 v99, v79
	s_nop 2
	v_cvt_pk_f16_f32 v91, v90, v91
	v_cvt_pk_f16_f32 v90, v88, v89
	v_cndmask_b32_e64 v97, 0, v97, s[10:11]
	v_cndmask_b32_e64 v98, v98, 0, s[18:19]
	v_mfma_f32_16x16x16_f16 v[84:87], v[0:1], v[90:91], 0
	v_add_u32_e32 v2, 0x800, v240
	ds_read2_b64 v[128:131], v2 offset0:64 offset1:144
	ds_read_b128 v[76:79], v182 offset:256
	v_mov_b32_e32 v90, v3
	v_mov_b32_e32 v91, v3
	v_cndmask_b32_e64 v99, v99, 0, s[22:23]
	ds_read_b64 v[88:89], v230 offset:5120
	ds_read_b128 v[132:135], v182 offset:320
	s_nop 3
	v_cvt_pk_f16_f32 v1, v86, v87
	v_cvt_pk_f16_f32 v0, v84, v85
	s_nop 0
	s_nop 0
	s_nop 0
	s_nop 0
	s_nop 0
	s_waitcnt lgkmcnt(3)
	v_mov_b32_e32 v92, v128
	v_mov_b32_e32 v93, v129
	ds_read_b64 v[84:85], v231 offset:5120
	s_nop 0
	s_waitcnt lgkmcnt(3)
	v_pk_mul_f32 v[42:43], v[42:43], v[78:79]
	v_pk_mul_f32 v[40:41], v[40:41], v[76:77]
	s_nop 0
	s_nop 0
	v_mfma_f32_16x16x16_f16 v[40:43], v[92:93], v[0:1], v[40:43]
	s_nop 0
	s_waitcnt lgkmcnt(1)
	v_pk_mul_f32 v[48:49], v[48:49], v[132:133]
	v_add_u32_e32 v76, 0xc00, v240
	ds_read2_b64 v[136:139], v76 offset0:96 offset1:176
	ds_read_b128 v[140:143], v182 offset:384
	v_mfma_f32_16x16x16_f16 v[40:43], v[88:89], v[36:37], v[40:43]
	v_mov_b32_e32 v88, v130
	v_mov_b32_e32 v89, v131
	v_pk_mul_f32 v[50:51], v[50:51], v[134:135]
	s_nop 0
	s_nop 0
	s_nop 0
	v_mfma_f32_16x16x16_f16 v[48:51], v[88:89], v[0:1], v[48:51]
	ds_read_b64 v[88:89], v232 offset:5120
	s_nop 0
	s_waitcnt lgkmcnt(2)
	v_mov_b32_e32 v92, v136
	v_mfma_f32_16x16x16_f16 v[48:51], v[84:85], v[36:37], v[48:51]
	s_nop 0
	s_nop 0
	v_mov_b32_e32 v93, v137
	v_pack_b32_f16 v76, v96, v97
	v_cndmask_b32_e64 v96, v56, 0, s[12:13]
	s_nop 0
	s_waitcnt lgkmcnt(1)
	v_pk_mul_f32 v[46:47], v[46:47], v[142:143]
	v_pk_mul_f32 v[44:45], v[44:45], v[140:141]
	ds_read_b128 v[84:87], v182 offset:448
	v_cvt_f16_f32_e32 v56, v57
	v_cvt_f16_f32_e32 v57, v58
	v_mfma_f32_16x16x16_f16 v[44:47], v[92:93], v[0:1], v[44:47]
	v_cvt_f16_f32_e32 v58, v59
	v_mov_b32_e32 v92, v138
	v_mov_b32_e32 v93, v139
	s_nop 0
	s_waitcnt lgkmcnt(1)
	v_mfma_f32_16x16x16_f16 v[44:47], v[88:89], v[36:37], v[44:47]
	ds_read_b64 v[88:89], v233 offset:5120
	s_nop 0
	s_nop 0
	v_cndmask_b32_e64 v78, v57, 0, s[18:19]
	v_cndmask_b32_e64 v79, v58, 0, s[22:23]
	v_pack_b32_f16 v77, v98, v99
	s_nop 0
	s_waitcnt lgkmcnt(1)
	v_pk_mul_f32 v[52:53], v[52:53], v[84:85]
	v_cndmask_b32_e64 v84, 0, v56, s[10:11]
	v_mfma_f32_16x16x32_f16 v[56:59], v[72:75], v[60:63], 0
	v_pack_b32_f16 v61, v78, v79
	v_mov_b32_e32 v78, v3
	v_mov_b32_e32 v79, v3
	v_mfma_f32_16x16x32_f16 v[56:59], v[68:71], v[64:67], v[56:59]
	v_mul_f32_e64 v54, v54, v86
	v_mul_f32_e64 v55, v55, v87
	v_pack_b32_f16 v60, v96, v84
	v_mov_b32_e32 v62, v3
	v_mov_b32_e32 v63, v3
	v_mfma_f32_16x16x16_f16 v[52:55], v[92:93], v[0:1], v[52:55]
	v_mfma_f32_16x16x16_f16 v[56:59], v[76:77], v[0:1], v[56:59]
	v_mad_i64_i32 v[0:1], s[28:29], v83, s88, v[126:127]
	global_store_short v[0:1], v82, off
	s_nop 0
	s_waitcnt lgkmcnt(0)
	v_mfma_f32_16x16x16_f16 v[52:55], v[88:89], v[36:37], v[52:55]
	v_subrev_u32_e32 v0, 48, v80
	v_add_u32_e32 v1, 0xef, v81
	v_cndmask_b32_e64 v0, v1, v0, s[2:3]
	v_mfma_f32_16x16x16_f16 v[36:39], v[60:61], v[36:37], v[56:59]
	v_add_u32_e32 v0, v0, v175
	v_mad_i64_i32 v[0:1], s[28:29], v0, s88, v[126:127]
	s_nop 5
	v_cvt_f16_f32_e32 v2, v36
	global_store_short v[0:1], v2, off
	v_subrev_u32_e32 v0, 47, v80
	v_add_u32_e32 v1, 0xee, v81
	v_cvt_f16_f32_e32 v2, v37
	v_cndmask_b32_e64 v0, v1, v0, s[2:3]
	v_add_u32_e32 v0, v0, v175
	v_mad_i64_i32 v[0:1], s[28:29], v0, s88, v[126:127]
	global_store_short v[0:1], v2, off
	v_subrev_u32_e32 v0, 46, v80
	v_add_u32_e32 v1, 0xed, v81
	v_cvt_f16_f32_e32 v2, v38
	v_cndmask_b32_e64 v0, v1, v0, s[2:3]
	v_add_u32_e32 v0, v0, v175
	v_mad_i64_i32 v[0:1], s[28:29], v0, s88, v[126:127]
	global_store_short v[0:1], v2, off
	v_subrev_u32_e32 v0, 45, v80
	v_add_u32_e32 v1, 0xec, v81
	v_cndmask_b32_e64 v0, v1, v0, s[2:3]
	v_cvt_f16_f32_e32 v2, v39
	v_add_u32_e32 v0, v0, v175
	v_mad_i64_i32 v[0:1], s[28:29], v0, s88, v[126:127]
	s_mov_b64 s[28:29], 0
	global_store_short v[0:1], v2, off

.LBB0_1035:
	s_or_b64 exec, exec, s[26:27]
	s_waitcnt lgkmcnt(0)
	s_barrier
	ds_read_b128 v[40:43], v212 offset:9216
	ds_read_b128 v[48:51], v212 offset:18496
	ds_read_b128 v[56:59], v212 offset:9280
	ds_read_b128 v[60:63], v212 offset:23040
	ds_read_b128 v[36:39], v212 offset:18432
	s_nop 0
	s_nop 0
	s_nop 0
	ds_read_b128 v[64:67], v212 offset:13824
	s_waitcnt lgkmcnt(1)
	v_mfma_f32_16x16x32_f16 v[52:55], v[40:43], v[36:39], 0
	s_nop 0
	s_nop 0
	s_nop 0
	ds_read_b128 v[68:71], v212 offset:13888
	ds_read_b128 v[72:75], v212 offset:23104
	v_add_u32_e32 v80, 0x1000, v217
	s_nop 0
	v_mfma_f32_16x16x32_f16 v[52:55], v[56:59], v[48:51], v[52:55]
	s_nop 0
	s_nop 0
	s_nop 0
	v_mfma_f32_16x16x32_f16 v[44:47], v[36:39], v[40:43], 0
	s_nop 3
	v_cvt_f16_f32_e32 v0, v52
	v_cvt_f16_f32_e32 v1, v54
	v_cvt_f16_f32_e32 v2, v55
	v_mfma_f32_16x16x32_f16 v[44:47], v[48:51], v[56:59], v[44:47]
	v_cndmask_b32_e64 v79, 0, v0, s[12:13]
	v_cvt_f16_f32_e32 v0, v53
	v_cndmask_b32_e64 v54, 0, v1, s[18:19]
	s_nop 0
	v_mfma_f32_16x16x32_f16 v[40:43], v[60:63], v[40:43], 0
	v_cndmask_b32_e64 v55, 0, v2, s[22:23]
	s_nop 1
	v_cndmask_b32_e64 v76, 0, v44, s[10:11]
	v_cndmask_b32_e64 v77, 0, v45, s[14:15]
	s_nop 0
	s_waitcnt lgkmcnt(2)
	v_mfma_f32_16x16x32_f16 v[36:39], v[36:39], v[64:67], 0
	v_cndmask_b32_e64 v52, 0, v46, s[16:17]
	v_cndmask_b32_e64 v78, 0, v47, s[20:21]
	v_cndmask_b32_e64 v53, v0, 0, s[10:11]
	v_mfma_f32_16x16x32_f16 v[44:47], v[60:63], v[64:67], 0
	v_cvt_pk_f16_f32 v1, v52, v78
	v_cvt_pk_f16_f32 v0, v76, v77
	s_nop 0
	s_nop 0
	s_waitcnt lgkmcnt(0)
	v_mfma_f32_16x16x32_f16 v[60:63], v[72:75], v[56:59], v[40:43]
	v_add_f32_e32 v56, v213, v76
	v_add_f32_e32 v57, v214, v77
	v_add_f32_e32 v58, v215, v52
	v_mfma_f32_16x16x32_f16 v[40:43], v[48:51], v[68:71], v[36:39]
	v_add_f32_e32 v59, v216, v78
	v_cvt_pk_f16_f32 v67, v18, v19
	v_cvt_pk_f16_f32 v66, v16, v17
	v_pack_b32_f16 v37, v54, v55
	v_pack_b32_f16 v36, v79, v53
	s_nop 0
	s_nop 0
	v_mfma_f32_16x16x32_f16 v[52:55], v[72:75], v[68:71], v[44:47]
	ds_read2_b64 v[68:71], v217 offset0:8 offset1:12
	v_cvt_pk_f16_f32 v65, v14, v15
	v_cvt_pk_f16_f32 v64, v12, v13
	v_mfma_f32_16x16x16_f16 v[48:51], v[0:1], v[36:37], 0
	v_cvt_pk_f16_f32 v45, v58, v59
	v_cvt_pk_f16_f32 v44, v56, v57
	s_nop 0
	v_mfma_f32_16x16x16_f16 v[36:39], v[36:37], v[0:1], 0
	s_nop 0
	s_nop 2
	v_cvt_pk_f16_f32 v1, v50, v51
	v_cvt_pk_f16_f32 v0, v48, v49
	s_nop 0
	s_nop 0
	v_cvt_pk_f16_f32 v49, v38, v39
	v_cvt_pk_f16_f32 v48, v36, v37
	v_mfma_f32_16x16x16_f16 v[44:47], v[0:1], v[44:45], v[56:59]
	s_nop 0
	s_nop 0
	s_nop 0
	v_mfma_f32_16x16x16_f16 v[36:39], v[48:49], v[0:1], 0
	ds_read2_b64 v[126:129], v217 offset1:4
	v_cvt_pk_f16_f32 v59, v10, v11
	v_cvt_pk_f16_f32 v58, v8, v9
	v_cvt_pk_f16_f32 v57, v6, v7
	v_mfma_f32_16x16x16_f16 v[48:51], v[0:1], v[48:49], 0
	v_cvt_pk_f16_f32 v56, v4, v5
	s_nop 2
	v_cvt_pk_f16_f32 v1, v38, v39
	v_cvt_pk_f16_f32 v0, v36, v37
	v_cvt_pk_f16_f32 v37, v46, v47
	v_cvt_pk_f16_f32 v36, v44, v45
	s_nop 0
	s_nop 0
	v_cvt_f16_f32_e32 v52, v52
	s_add_i32 s28, s76, 1
	v_mfma_f32_16x16x16_f16 v[44:47], v[0:1], v[36:37], v[44:47]
	v_cvt_pk_f16_f32 v37, v50, v51
	v_cvt_pk_f16_f32 v36, v48, v49
	s_nop 0
	s_nop 0
	v_mfma_f32_16x16x16_f16 v[36:39], v[36:37], v[0:1], 0
	s_nop 2
	v_cvt_pk_f16_f32 v1, v46, v47
	v_cvt_pk_f16_f32 v0, v44, v45
	s_nop 2
	v_cvt_pk_f16_f32 v49, v38, v39
	v_cvt_pk_f16_f32 v48, v36, v37
	s_nop 0
	s_nop 0
	s_waitcnt lgkmcnt(0)
	v_mfma_f32_16x16x32_f16 v[36:39], v[126:129], v[56:59], 0
	v_mfma_f32_16x16x16_f16 v[44:47], v[48:49], v[0:1], v[44:47]
	v_cvt_f16_f32_e32 v0, v60
	v_cvt_f16_f32_e32 v1, v61
	v_cvt_f16_f32_e32 v2, v62
	v_cvt_f16_f32_e32 v48, v63
	v_mfma_f32_16x16x32_f16 v[76:79], v[68:71], v[64:67], v[36:39]
	ds_read2_b64 v[72:75], v80 offset0:64 offset1:68
	ds_read2st64_b64 v[130:133], v218 offset0:20 offset1:25
	ds_read2_b64 v[68:71], v80 offset0:72 offset1:76
	s_nop 0
	s_nop 0
	v_cndmask_b32_e64 v0, 0, v0, s[10:11]
	v_cndmask_b32_e64 v49, 0, v1, s[14:15]
	v_cndmask_b32_e64 v1, 0, v2, s[16:17]
	v_cndmask_b32_e64 v2, 0, v48, s[20:21]
	v_pack_b32_f16 v1, v1, v2
	v_pack_b32_f16 v0, v0, v49
	s_nop 0
	s_nop 0
	s_waitcnt lgkmcnt(1)
	v_mov_b32_e32 v60, v130
	v_mov_b32_e32 v61, v131
	ds_read2_b64 v[126:129], v233 offset1:80
	s_nop 0
	s_nop 0
	v_cvt_f16_f32_e32 v36, v40
	ds_read_b128 v[134:137], v178
	v_cvt_f16_f32_e32 v40, v42
	v_mfma_f32_16x16x16_f16 v[48:51], v[0:1], v[60:61], v[76:79]
	v_cvt_pk_f16_f32 v1, v46, v47
	v_cvt_pk_f16_f32 v0, v44, v45
	v_cvt_f16_f32_e32 v37, v41
	s_nop 0
	s_nop 0
	s_nop 2
	v_cvt_pk_f16_f32 v77, v50, v51
	v_cvt_pk_f16_f32 v76, v48, v49
	v_cndmask_b32_e64 v88, v40, 0, s[18:19]
	v_mfma_f32_16x16x32_f16 v[56:59], v[72:75], v[56:59], 0
	v_cndmask_b32_e64 v36, v36, 0, s[12:13]
	v_cndmask_b32_e64 v37, 0, v37, s[10:11]
	s_nop 0
	v_mfma_f32_16x16x16_f16 v[44:47], v[0:1], v[76:77], 0
	ds_read_b64 v[76:77], v219 offset:5120
	ds_read_b128 v[138:141], v178 offset:64
	s_nop 0
	s_waitcnt lgkmcnt(4)
	v_mfma_f32_16x16x32_f16 v[56:59], v[68:71], v[64:67], v[56:59]
	s_nop 5
	v_cvt_pk_f16_f32 v1, v46, v47
	v_cvt_pk_f16_f32 v0, v44, v45
	s_nop 0
	s_nop 0
	s_nop 0
	s_nop 0
	s_waitcnt lgkmcnt(3)
	v_mov_b32_e32 v80, v126
	v_mov_b32_e32 v81, v127
	ds_read_b64 v[44:45], v220 offset:5120
	ds_read2_b64 v[142:145], v233 offset0:160 offset1:240
	s_nop 0
	s_waitcnt lgkmcnt(4)
	v_pk_mul_f32 v[50:51], v[6:7], v[136:137]
	v_pk_mul_f32 v[48:49], v[4:5], v[134:135]
	ds_read_b128 v[134:137], v178 offset:128
	s_nop 1
	v_mfma_f32_16x16x16_f16 v[48:51], v[80:81], v[0:1], v[48:51]
	v_cvt_f16_f32_e32 v80, v43
	v_cndmask_b32_e64 v89, v80, 0, s[22:23]
	s_nop 0
	s_waitcnt lgkmcnt(4)
	v_mfma_f32_16x16x16_f16 v[40:43], v[76:77], v[60:61], v[48:51]
	s_nop 3
	s_nop 0
	s_nop 0
	ds_read_b64 v[80:81], v221 offset:5120
	v_mov_b32_e32 v76, v128
	v_mov_b32_e32 v77, v129
	s_nop 0
	s_nop 0
	s_waitcnt lgkmcnt(4)
	v_pk_mul_f32 v[50:51], v[10:11], v[140:141]
	v_pk_mul_f32 v[48:49], v[8:9], v[138:139]
	s_nop 0
	ds_read_b128 v[126:129], v178 offset:192
	s_nop 0
	v_mfma_f32_16x16x16_f16 v[48:51], v[76:77], v[0:1], v[48:51]
	s_nop 0
	s_nop 0
	s_waitcnt lgkmcnt(3)
	v_mov_b32_e32 v84, v142
	v_mfma_f32_16x16x16_f16 v[48:51], v[44:45], v[60:61], v[48:51]
	s_nop 0
	s_nop 0
	v_mov_b32_e32 v85, v143
	v_pack_b32_f16 v77, v88, v89
	v_mov_b32_e32 v88, v144
	s_nop 0
	s_waitcnt lgkmcnt(2)
	v_pk_mul_f32 v[46:47], v[14:15], v[136:137]
	v_pk_mul_f32 v[44:45], v[12:13], v[134:135]
	v_mov_b32_e32 v89, v145
	v_pack_b32_f16 v76, v36, v37
	v_mfma_f32_16x16x16_f16 v[44:47], v[84:85], v[0:1], v[44:47]
	ds_read_b64 v[84:85], v222 offset:5120
	v_cndmask_b32_e64 v36, v52, 0, s[12:13]
	v_cvt_f16_f32_e32 v37, v53
	v_cndmask_b32_e64 v37, 0, v37, s[10:11]
	s_nop 0
	s_waitcnt lgkmcnt(2)
	v_mfma_f32_16x16x16_f16 v[44:47], v[80:81], v[60:61], v[44:47]
	s_nop 0
	s_nop 0
	v_pack_b32_f16 v72, v36, v37
	ds_read_b128 v[68:71], v223 offset:9216
	ds_read_b128 v[94:97], v223 offset:9280
	s_nop 0
	s_waitcnt lgkmcnt(3)
	v_pk_mul_f32 v[82:83], v[18:19], v[128:129]
	ds_read_b128 v[64:67], v223 offset:18432
	v_pk_mul_f32 v[80:81], v[16:17], v[126:127]
	s_nop 0
	ds_read_b128 v[98:101], v223 offset:23104
	v_mfma_f32_16x16x16_f16 v[78:81], v[88:89], v[0:1], v[80:83]
	ds_read_b128 v[90:93], v223 offset:18496
	s_nop 1
	v_cvt_f16_f32_e32 v82, v54
	v_cvt_f16_f32_e32 v83, v55
	s_nop 0
	s_waitcnt lgkmcnt(5)
	v_mfma_f32_16x16x16_f16 v[52:55], v[84:85], v[60:61], v[78:81]
	ds_read_b128 v[86:89], v223 offset:13824
	s_nop 1
	v_cndmask_b32_e64 v78, v82, 0, s[18:19]
	v_cndmask_b32_e64 v79, v83, 0, s[22:23]
	v_pack_b32_f16 v73, v78, v79
	s_nop 0
	s_nop 0
	v_add_u32_e32 v80, s69, v153
	v_add_u32_e32 v81, s68, v232
	v_mfma_f32_16x16x16_f16 v[56:59], v[76:77], v[0:1], v[56:59]
	ds_read_b128 v[76:79], v223 offset:23040
	v_subrev_u32_e32 v102, 64, v80
	v_add_u32_e32 v0, 0x7ff, v81
	v_mfma_f32_16x16x16_f16 v[58:61], v[72:73], v[60:61], v[56:59]
	v_cndmask_b32_e64 v0, v0, v102, s[2:3]
	v_add_u32_e32 v0, v0, v151
	v_mad_i64_i32 v[0:1], s[26:27], v0, s88, v[122:123]
	s_nop 0
	s_waitcnt lgkmcnt(4)
	v_mfma_f32_16x16x32_f16 v[82:85], v[68:71], v[64:67], 0
	s_nop 2
	v_cvt_f16_f32_e32 v2, v58
	v_cvt_f16_f32_e32 v60, v60
	ds_read_b128 v[126:129], v223 offset:13888
	global_store_short v[0:1], v2, off
	v_subrev_u32_e32 v0, 63, v80
	v_xad_u32 v1, v102, -2, v172
	v_cvt_f16_f32_e32 v2, v59
	s_nop 0
	v_mfma_f32_16x16x32_f16 v[72:75], v[64:67], v[68:71], 0
	v_cndmask_b32_e64 v0, v1, v0, s[2:3]
	v_add_u32_e32 v0, v0, v151
	v_mad_i64_i32 v[0:1], s[26:27], v0, s88, v[122:123]
	s_nop 0
	s_waitcnt lgkmcnt(2)
	v_mfma_f32_16x16x32_f16 v[62:65], v[64:67], v[86:89], 0
	global_store_short v[0:1], v2, off
	v_subrev_u32_e32 v0, 62, v80
	v_xad_u32 v1, v102, -3, v172
	v_mfma_f32_16x16x32_f16 v[82:85], v[94:97], v[90:93], v[82:85]
	v_cndmask_b32_e64 v36, v1, v0, s[2:3]
	v_add_u32_e32 v36, v36, v151
	s_nop 0
	s_waitcnt lgkmcnt(1)
	v_mfma_f32_16x16x32_f16 v[68:71], v[76:79], v[68:71], 0
	v_mfma_f32_16x16x32_f16 v[86:89], v[76:79], v[86:89], 0
	s_nop 2
	v_cvt_f16_f32_e32 v1, v82
	v_cvt_f16_f32_e32 v2, v83
	v_cvt_f16_f32_e32 v66, v85
	v_mfma_f32_16x16x32_f16 v[72:75], v[90:93], v[94:97], v[72:75]
	s_nop 0
	v_cndmask_b32_e64 v66, 0, v66, s[22:23]
	s_nop 0
	s_waitcnt lgkmcnt(0)
	v_mfma_f32_16x16x32_f16 v[76:79], v[90:93], v[126:129], v[62:65]
	s_nop 0
	s_nop 2
	v_cndmask_b32_e64 v0, 0, v72, s[10:11]
	v_cndmask_b32_e64 v37, 0, v73, s[14:15]
	v_cvt_f16_f32_e32 v63, v84
	v_mfma_f32_16x16x32_f16 v[94:97], v[98:101], v[94:97], v[68:71]
	v_cndmask_b32_e64 v64, 0, v74, s[16:17]
	v_cndmask_b32_e64 v65, 0, v75, s[20:21]
	v_cndmask_b32_e64 v63, 0, v63, s[18:19]
	v_cndmask_b32_e64 v68, 0, v1, s[12:13]
	v_cndmask_b32_e64 v69, v2, 0, s[10:11]
	v_add_f32_e32 v62, v213, v0
	v_cvt_pk_f16_f32 v1, v64, v65
	v_cvt_pk_f16_f32 v0, v0, v37
	s_nop 0
	v_pack_b32_f16 v67, v63, v66
	v_pack_b32_f16 v66, v68, v69
	s_nop 0
	s_nop 0
	v_add_f32_e32 v63, v214, v37
	v_add_f32_e32 v64, v215, v64
	v_mfma_f32_16x16x16_f16 v[70:73], v[0:1], v[66:67], 0
	v_add_f32_e32 v65, v216, v65
	v_cvt_pk_f16_f32 v83, v64, v65
	v_cvt_pk_f16_f32 v82, v62, v63
	v_mfma_f32_16x16x16_f16 v[66:69], v[66:67], v[0:1], 0
	s_nop 0
	s_nop 2
	v_cvt_pk_f16_f32 v0, v70, v71
	s_nop 0
	s_nop 0
	v_cvt_pk_f16_f32 v1, v72, v73
	v_cvt_pk_f16_f32 v69, v68, v69
	v_cvt_pk_f16_f32 v68, v66, v67
	v_mfma_f32_16x16x16_f16 v[62:65], v[0:1], v[82:83], v[62:65]
	v_mad_i64_i32 v[36:37], s[26:27], v36, s88, v[122:123]
	global_store_short v[36:37], v60, off
	v_mfma_f32_16x16x16_f16 v[72:75], v[68:69], v[0:1], 0
	v_cvt_f16_f32_e32 v82, v61
	v_subrev_u32_e32 v36, 61, v80
	v_xad_u32 v37, v102, -4, v172
	v_mfma_f32_16x16x16_f16 v[66:69], v[0:1], v[68:69], 0
	s_nop 0
	v_cvt_pk_f16_f32 v71, v64, v65
	s_nop 1
	v_cvt_pk_f16_f32 v1, v74, v75
	v_cvt_pk_f16_f32 v0, v72, v73
	ds_read2_b64 v[134:137], v224 offset1:4
	v_mfma_f32_16x16x32_f16 v[56:59], v[98:101], v[126:129], v[86:89]
	v_cvt_pk_f16_f32 v70, v62, v63
	s_nop 0
	s_nop 0
	v_cvt_pk_f16_f32 v85, v68, v69
	ds_read2_b64 v[126:129], v224 offset0:8 offset1:12
	v_cvt_pk_f16_f32 v84, v66, v67
	s_nop 0
	s_nop 0
	v_mfma_f32_16x16x16_f16 v[88:91], v[0:1], v[70:71], v[62:65]
	s_nop 0
	s_nop 0
	v_cndmask_b32_e64 v36, v37, v36, s[2:3]
	v_mfma_f32_16x16x16_f16 v[60:63], v[84:85], v[0:1], 0
	v_add_u32_e32 v83, v36, v151
	s_nop 2
	v_cvt_pk_f16_f32 v1, v90, v91
	v_cvt_pk_f16_f32 v0, v88, v89
	v_cvt_pk_f16_f32 v67, v54, v55
	v_cvt_pk_f16_f32 v66, v52, v53
	v_cvt_pk_f16_f32 v85, v62, v63
	v_cvt_pk_f16_f32 v84, v60, v61
	v_cvt_pk_f16_f32 v63, v50, v51
	v_cvt_pk_f16_f32 v62, v48, v49
	v_cvt_pk_f16_f32 v61, v42, v43
	v_cvt_pk_f16_f32 v60, v40, v41
	v_cvt_pk_f16_f32 v65, v46, v47
	v_cvt_pk_f16_f32 v64, v44, v45
	s_nop 0
	s_waitcnt lgkmcnt(1)
	v_mfma_f32_16x16x32_f16 v[68:71], v[134:137], v[60:63], 0
	v_add_u32_e32 v36, 0x1000, v224
	s_nop 0
	v_cvt_f16_f32_e32 v76, v76
	s_nop 0
	s_waitcnt lgkmcnt(0)
	v_mfma_f32_16x16x32_f16 v[98:101], v[126:129], v[64:67], v[68:71]
	ds_read2_b64 v[72:75], v36 offset0:64 offset1:68
	s_nop 1
	ds_read2_b64 v[68:71], v36 offset0:72 offset1:76
	v_cvt_f16_f32_e32 v36, v97
	v_cvt_f16_f32_e32 v97, v77
	v_mfma_f32_16x16x16_f16 v[84:87], v[84:85], v[0:1], v[88:91]
	v_cvt_f16_f32_e32 v0, v94
	v_cvt_f16_f32_e32 v1, v95
	v_cvt_f16_f32_e32 v2, v96
	v_cndmask_b32_e64 v96, v76, 0, s[12:13]
	v_cndmask_b32_e64 v0, 0, v0, s[10:11]
	v_cndmask_b32_e64 v37, 0, v1, s[14:15]
	v_cndmask_b32_e64 v1, 0, v2, s[16:17]
	v_cndmask_b32_e64 v2, 0, v36, s[20:21]
	v_pack_b32_f16 v1, v1, v2
	v_pack_b32_f16 v0, v0, v37
	s_nop 0
	v_mov_b32_e32 v36, v132
	v_mov_b32_e32 v37, v133
	s_nop 0
	s_nop 0
	v_mov_b32_e32 v94, v3
	v_mov_b32_e32 v95, v3
	v_mfma_f32_16x16x16_f16 v[88:91], v[0:1], v[36:37], v[98:101]
	v_cvt_pk_f16_f32 v1, v86, v87
	v_cvt_pk_f16_f32 v0, v84, v85
	v_cvt_f16_f32_e32 v56, v56
	v_cvt_f16_f32_e32 v98, v78
	v_cvt_f16_f32_e32 v99, v79
	s_nop 2
	v_cvt_pk_f16_f32 v91, v90, v91
	v_cvt_pk_f16_f32 v90, v88, v89
	v_cndmask_b32_e64 v97, 0, v97, s[10:11]
	v_cndmask_b32_e64 v98, v98, 0, s[18:19]
	v_mfma_f32_16x16x16_f16 v[84:87], v[0:1], v[90:91], 0
	v_add_u32_e32 v2, 0x800, v233
	ds_read2_b64 v[126:129], v2 offset0:64 offset1:144
	ds_read_b128 v[76:79], v178 offset:256
	v_mov_b32_e32 v90, v3
	v_mov_b32_e32 v91, v3
	v_cndmask_b32_e64 v99, v99, 0, s[22:23]
	ds_read_b64 v[88:89], v225 offset:5120
	ds_read_b128 v[130:133], v178 offset:320
	s_nop 3
	v_cvt_pk_f16_f32 v1, v86, v87
	v_cvt_pk_f16_f32 v0, v84, v85
	s_nop 0
	s_nop 0
	s_nop 0
	s_nop 0
	s_nop 0
	s_waitcnt lgkmcnt(3)
	v_mov_b32_e32 v92, v126
	v_mov_b32_e32 v93, v127
	ds_read_b64 v[84:85], v226 offset:5120
	s_nop 0
	s_waitcnt lgkmcnt(3)
	v_pk_mul_f32 v[42:43], v[42:43], v[78:79]
	v_pk_mul_f32 v[40:41], v[40:41], v[76:77]
	s_nop 0
	s_nop 0
	v_mfma_f32_16x16x16_f16 v[40:43], v[92:93], v[0:1], v[40:43]
	s_nop 0
	s_waitcnt lgkmcnt(1)
	v_pk_mul_f32 v[48:49], v[48:49], v[130:131]
	v_add_u32_e32 v76, 0xc00, v233
	ds_read2_b64 v[134:137], v76 offset0:96 offset1:176
	ds_read_b128 v[138:141], v178 offset:384
	v_mfma_f32_16x16x16_f16 v[40:43], v[88:89], v[36:37], v[40:43]
	v_mov_b32_e32 v88, v128
	v_mov_b32_e32 v89, v129
	v_pk_mul_f32 v[50:51], v[50:51], v[132:133]
	s_nop 0
	s_nop 0
	s_nop 0
	v_mfma_f32_16x16x16_f16 v[48:51], v[88:89], v[0:1], v[48:51]
	ds_read_b64 v[88:89], v227 offset:5120
	s_nop 0
	s_waitcnt lgkmcnt(2)
	v_mov_b32_e32 v92, v134
	v_mfma_f32_16x16x16_f16 v[48:51], v[84:85], v[36:37], v[48:51]
	s_nop 0
	s_nop 0
	v_mov_b32_e32 v93, v135
	v_pack_b32_f16 v76, v96, v97
	v_cndmask_b32_e64 v96, v56, 0, s[12:13]
	s_nop 0
	s_waitcnt lgkmcnt(1)
	v_pk_mul_f32 v[46:47], v[46:47], v[140:141]
	v_pk_mul_f32 v[44:45], v[44:45], v[138:139]
	ds_read_b128 v[84:87], v178 offset:448
	v_cvt_f16_f32_e32 v56, v57
	v_cvt_f16_f32_e32 v57, v58
	v_mfma_f32_16x16x16_f16 v[44:47], v[92:93], v[0:1], v[44:47]
	v_cvt_f16_f32_e32 v58, v59
	v_mov_b32_e32 v92, v136
	v_mov_b32_e32 v93, v137
	s_nop 0
	s_waitcnt lgkmcnt(1)
	v_mfma_f32_16x16x16_f16 v[44:47], v[88:89], v[36:37], v[44:47]
	ds_read_b64 v[88:89], v228 offset:5120
	s_nop 0
	s_nop 0
	v_cndmask_b32_e64 v78, v57, 0, s[18:19]
	v_cndmask_b32_e64 v79, v58, 0, s[22:23]
	v_pack_b32_f16 v77, v98, v99
	s_nop 0
	s_waitcnt lgkmcnt(1)
	v_pk_mul_f32 v[52:53], v[52:53], v[84:85]
	v_cndmask_b32_e64 v84, 0, v56, s[10:11]
	v_mfma_f32_16x16x32_f16 v[56:59], v[72:75], v[60:63], 0
	v_pack_b32_f16 v61, v78, v79
	v_mov_b32_e32 v78, v3
	v_mov_b32_e32 v79, v3
	v_mfma_f32_16x16x32_f16 v[56:59], v[68:71], v[64:67], v[56:59]
	v_mul_f32_e64 v54, v54, v86
	v_mul_f32_e64 v55, v55, v87
	v_pack_b32_f16 v60, v96, v84
	v_mov_b32_e32 v62, v3
	v_mov_b32_e32 v63, v3
	v_mfma_f32_16x16x16_f16 v[52:55], v[92:93], v[0:1], v[52:55]
	v_mfma_f32_16x16x16_f16 v[56:59], v[76:77], v[0:1], v[56:59]
	v_mad_i64_i32 v[0:1], s[26:27], v83, s88, v[122:123]
	global_store_short v[0:1], v82, off
	s_nop 0
	s_waitcnt lgkmcnt(0)
	v_mfma_f32_16x16x16_f16 v[52:55], v[88:89], v[36:37], v[52:55]
	v_subrev_u32_e32 v0, 48, v80
	v_add_u32_e32 v1, 0x7ef, v81
	v_cndmask_b32_e64 v0, v1, v0, s[2:3]
	v_mfma_f32_16x16x16_f16 v[36:39], v[60:61], v[36:37], v[56:59]
	v_add_u32_e32 v0, v0, v151
	v_mad_i64_i32 v[0:1], s[26:27], v0, s88, v[122:123]
	s_nop 5
	v_cvt_f16_f32_e32 v2, v36
	global_store_short v[0:1], v2, off
	v_subrev_u32_e32 v0, 47, v80
	v_add_u32_e32 v1, 0x7ee, v81
	v_cvt_f16_f32_e32 v2, v37
	v_cndmask_b32_e64 v0, v1, v0, s[2:3]
	v_add_u32_e32 v0, v0, v151
	v_mad_i64_i32 v[0:1], s[26:27], v0, s88, v[122:123]
	global_store_short v[0:1], v2, off
	v_subrev_u32_e32 v0, 46, v80
	v_add_u32_e32 v1, 0x7ed, v81
	v_cvt_f16_f32_e32 v2, v38
	v_cndmask_b32_e64 v0, v1, v0, s[2:3]
	v_add_u32_e32 v0, v0, v151
	v_mad_i64_i32 v[0:1], s[26:27], v0, s88, v[122:123]
	global_store_short v[0:1], v2, off
	v_subrev_u32_e32 v0, 45, v80
	v_add_u32_e32 v1, 0x7ec, v81
	v_cndmask_b32_e64 v0, v1, v0, s[2:3]
	v_cvt_f16_f32_e32 v2, v39
	v_add_u32_e32 v0, v0, v151
	v_mad_i64_i32 v[0:1], s[26:27], v0, s88, v[122:123]
	s_mov_b64 s[26:27], 0
	global_store_short v[0:1], v2, off
